# ret_out cross term streams chunk-state fragments 8 loads deep; merge-GEMM mid hook gate loads pipelined 3 groups ahead; SWA prefetch
# speedup vs baseline: 1.0280x; 1.0280x over previous
; #define LAS __attribute__((address_space(3)))
; __device__ __forceinline__ float ret_logg(int h) { return log1pf(-exp2f(-5.f - (float)h)); }
; template <bool ZETA>
; __device__ __forceinline__ void ret_stage(const Params& p, LAS unsigned char* lds, int tb, int h, int c, float logg, int tid) {
;     const half_t* PR = (const half_t*)(p.ws + WS_PROJ); const float* rot = (const float*)(p.ws + WS_ROT);
;     LAS half_t* Ks = (LAS half_t*)lds; LAS half_t* Vs = (LAS half_t*)(lds + RV_OFF);
; #pragma unroll
;     for (int i = 0; i < 2; ++i) { const int id = tid + 512 * i, pos = id >> 3, ch = id & 7;
;         const half_t* src = PR + (size_t)(tb + pos) * NIN + C_RK + h * 128 + ch * 8;
;         const h8 x1 = *(const h8*)src, x2 = *(const h8*)(src + 64);
;         const float* cp = rot + (size_t)(c * 128 + pos) * 64 + ch * 8; const float* sp = cp + SEQ * 64;
;         const f32x4 c0 = *(const f32x4*)cp, c1 = *(const f32x4*)(cp + 4), s0 = *(const f32x4*)sp, s1 = *(const f32x4*)(sp + 4);
; __device__ __forceinline__ void ret_out_item(const Params& p, int l, LAS unsigned char* lds, int item, int tid, int wave, int lane) {
;     const int b = item >> 8, h = (item >> 5) & 7, c = item & 31, tb = b * SEQ + c * 128;
;     const float logg = ret_logg(h);
;     const half_t* PR = (const half_t*)(p.ws + WS_PROJ); const float* rot = (const float*)(p.ws + WS_ROT);
;     const LAS half_t* Ks = (const LAS half_t*)lds; const LAS half_t* Vs = (const LAS half_t*)(lds + RV_OFF);
;     const int g = lane >> 4, r = lane & 15, q = (lane & 15) >> 2, pp = lane & 3;
;     const int ntile = wave < 4 ? wave : 11 - wave;
;     const int n0 = ntile * 16, nq = n0 + r, tok = tb + nq;
;     h8 xq[4]; f32x4 rc[2][2], rs[2][2];
; #pragma unroll
;     for (int ks = 0; ks < 4; ++ks) xq[ks] = *(const h8*)(PR + (size_t)tok * NIN + C_RQ + h * 128 + ks * 32 + g * 8);
; #pragma unroll
;     for (int ks = 0; ks < 2; ++ks) { const float* cp = rot + (size_t)(c * 128 + nq) * 64 + ks * 32 + g * 8; const float* sp = cp + SEQ * 64;
;         rc[ks][0] = *(const f32x4*)cp; rc[ks][1] = *(const f32x4*)(cp + 4); rs[ks][0] = *(const f32x4*)sp; rs[ks][1] = *(const f32x4*)(sp + 4); }
.LBB0_523:
	s_bfe_u32 s48, s47, 0x30005
	v_cvt_f32_ubyte0_e32 v4, s48
	v_sub_f32_e32 v4, 0xc0a00000, v4
	s_mov_b32 s20, 0xc2fc0000
	v_cmp_gt_f32_e32 vcc, s20, v4
	s_and_b32 s8, s47, 31
	s_and_b32 s9, s46, 0xfffff000
	v_cndmask_b32_e32 v5, 0, v185, vcc
	v_add_f32_e32 v4, v4, v5
	s_lshl_b32 s49, s8, 7
	v_exp_f32_e32 v4, v4
	s_or_b32 s9, s9, s49
	s_and_b64 vcc, vcc, exec
	s_cselect_b32 s20, 0xffffffc0, 0
	v_ldexp_f32 v82, v4, s20
	v_sub_f32_e32 v6, 1.0, v82
	v_add_f32_e32 v4, -1.0, v6
	v_sub_f32_e32 v5, v4, v6
	v_add_f32_e32 v5, 1.0, v5
	v_sub_f32_e64 v4, -v82, v4
	v_add_f32_e32 v7, v4, v5
	v_frexp_mant_f32_e32 v8, v6
	v_cvt_f64_f32_e32 v[4:5], v6
	s_mov_b32 s20, 0x3f2aaaab
	v_frexp_exp_i32_f64_e32 v4, v[4:5]
	v_cmp_gt_f32_e32 vcc, s20, v8
	v_mov_b64_e32 v[68:69], s[36:37]
	s_lshl_b32 s20, s48, 8
	v_subbrev_co_u32_e32 v4, vcc, 0, v4, vcc
	v_sub_u32_e32 v5, 0, v4
	v_ldexp_f32 v6, v6, v5
	v_ldexp_f32 v5, v7, v5
	v_add_f32_e32 v7, -1.0, v6
	v_add_f32_e32 v10, 1.0, v6
	v_add_f32_e32 v8, 1.0, v7
	v_add_f32_e32 v11, -1.0, v10
	v_sub_f32_e32 v8, v6, v8
	v_sub_f32_e32 v6, v6, v11
	v_add_f32_e32 v8, v5, v8
	v_add_f32_e32 v5, v5, v6
	v_add_f32_e32 v6, v10, v5
	v_rcp_f32_e32 v11, v6
	v_add_f32_e32 v9, v7, v8
	v_sub_f32_e32 v7, v9, v7
	v_sub_f32_e32 v7, v8, v7
	v_sub_f32_e32 v8, v6, v10
	v_sub_f32_e32 v5, v5, v8
	v_mul_f32_e32 v8, v9, v11
	v_mul_f32_e32 v10, v6, v8
	v_fma_f32 v12, v8, v6, -v10
	v_fmac_f32_e32 v12, v8, v5
	v_add_f32_e32 v13, v10, v12
	v_sub_f32_e32 v14, v9, v13
	v_sub_f32_e32 v9, v9, v14
	v_sub_f32_e32 v10, v13, v10
	v_sub_f32_e32 v9, v9, v13
	v_add_f32_e32 v7, v7, v9
	v_sub_f32_e32 v9, v10, v12
	v_add_f32_e32 v7, v9, v7
	v_add_f32_e32 v9, v14, v7
	v_mul_f32_e32 v10, v11, v9
	v_mul_f32_e32 v12, v6, v10
	v_fma_f32 v6, v10, v6, -v12
	v_fmac_f32_e32 v6, v10, v5
	v_sub_f32_e32 v5, v14, v9
	v_add_f32_e32 v5, v7, v5
	v_add_f32_e32 v7, v12, v6
	v_sub_f32_e32 v13, v9, v7
	v_sub_f32_e32 v9, v9, v13
	v_sub_f32_e32 v12, v7, v12
	v_sub_f32_e32 v7, v9, v7
	v_add_f32_e32 v5, v5, v7
	v_sub_f32_e32 v6, v12, v6
	v_add_f32_e32 v5, v6, v5
	v_add_f32_e32 v9, v8, v10
	v_add_f32_e32 v5, v13, v5
	v_sub_f32_e32 v6, v9, v8
	v_mul_f32_e32 v5, v11, v5
	v_sub_f32_e32 v6, v10, v6
	v_cvt_f32_i32_e32 v12, v4
	v_add_u32_e32 v4, s9, v125
	v_add_f32_e32 v8, v6, v5
	v_mad_i64_i32 v[4:5], vcc, v4, s35, v[68:69]
	v_lshl_add_u64 v[4:5], v[4:5], 0, s[20:21]
	v_mov_b32_e32 v93, v3
	v_lshl_add_u64 v[4:5], v[4:5], 0, v[92:93]
	global_load_dwordx4 v[56:59], v[4:5], off offset:2048
	global_load_dwordx4 v[52:55], v[4:5], off offset:2176
	v_add_u32_e32 v4, s49, v125
	v_ashrrev_i32_e32 v5, 31, v4
	v_lshlrev_b64 v[4:5], 8, v[4:5]
	v_lshl_add_u64 v[4:5], v[88:89], 0, v[4:5]
	s_mov_b32 s52, 0x100000
	v_add_co_u32_e32 v6, vcc, s52, v4
	s_mov_b64 s[54:55], 0x100000
	s_nop 0
	v_addc_co_u32_e32 v7, vcc, 0, v5, vcc
	global_load_dwordx4 v[70:73], v[6:7], off
	global_load_dwordx4 v[60:63], v[4:5], off offset:16
	global_load_dwordx4 v[74:77], v[4:5], off
	v_lshl_add_u64 v[4:5], v[4:5], 0, s[54:55]
	global_load_dwordx4 v[64:67], v[4:5], off offset:16
	v_add_f32_e32 v10, v9, v8
	v_mul_f32_e32 v11, v10, v10
	v_mul_f32_e32 v7, 0x3f317218, v12
	s_mov_b32 s60, 0x3f317218
	v_fmamk_f32 v6, v11, 0x3e9b6dac, v184
	v_fma_f32 v13, v12, s60, -v7
	v_fmaak_f32 v6, v11, v6, 0x3f2aaada
	v_fmac_f32_e32 v13, 0xb102e308, v12
	v_sub_f32_e32 v9, v10, v9
	v_ldexp_f32 v12, v10, 1
	v_mul_f32_e32 v10, v10, v11
	v_mul_f32_e32 v6, v10, v6
	v_add_f32_e32 v10, v12, v6
	v_sub_f32_e32 v8, v8, v9
	v_sub_f32_e32 v11, v10, v12
	v_ldexp_f32 v8, v8, 1
	v_sub_f32_e32 v6, v6, v11
	v_add_f32_e32 v6, v8, v6
	v_add_f32_e32 v9, v7, v13
	v_add_f32_e32 v8, v10, v6
	v_add_f32_e32 v4, v9, v8
	v_sub_f32_e32 v10, v8, v10
	v_sub_f32_e32 v5, v4, v9
	v_sub_f32_e32 v7, v9, v7
	v_sub_f32_e32 v6, v6, v10
	v_sub_f32_e32 v10, v4, v5
	v_sub_f32_e32 v7, v13, v7
	v_sub_f32_e32 v9, v9, v10
	v_sub_f32_e32 v5, v8, v5
	v_add_f32_e32 v5, v5, v9
	v_add_f32_e32 v8, v7, v6
	v_sub_f32_e32 v9, v8, v7
	v_add_f32_e32 v5, v8, v5
	v_sub_f32_e32 v10, v8, v9
	v_add_f32_e32 v12, v4, v5
	v_sub_f32_e32 v7, v7, v10
	v_sub_f32_e32 v6, v6, v9
	v_sub_f32_e32 v4, v12, v4
	v_add_f32_e32 v6, v6, v7
	v_sub_f32_e32 v4, v5, v4
	v_add_u32_e32 v96, s9, v124
	v_add_f32_e32 v13, v6, v4
	v_mad_i64_i32 v[98:99], vcc, v96, s35, v[68:69]
	v_add_f32_e32 v12, v12, v13
	v_cmp_nlt_f32_e32 vcc, 1.0, v82
	v_lshl_add_u64 v[4:5], v[98:99], 0, s[20:21]
	v_lshl_add_u64 v[8:9], v[4:5], 0, v[2:3]
	v_cndmask_b32_e32 v12, v186, v12, vcc
	v_cmp_neq_f32_e32 vcc, 1.0, v82
	global_load_dwordx4 v[32:35], v[8:9], off
	global_load_dwordx4 v[4:7], v[8:9], off offset:64
	global_load_dwordx4 v[40:43], v[8:9], off offset:128
	s_nop 0
	global_load_dwordx4 v[8:11], v[8:9], off offset:192
	v_cndmask_b32_e32 v83, v187, v12, vcc
	v_add_u32_e32 v12, s49, v124
	v_ashrrev_i32_e32 v13, 31, v12
	v_lshlrev_b64 v[12:13], 8, v[12:13]
	v_lshl_add_u64 v[16:17], v[0:1], 0, v[12:13]
	v_add_co_u32_e32 v18, vcc, s52, v16
	v_lshl_add_u64 v[12:13], v[16:17], 0, s[54:55]
	s_nop 0
	v_addc_co_u32_e32 v19, vcc, 0, v17, vcc
	s_mov_b64 vcc, 0x100080
	s_nop 0
	v_lshl_add_u64 v[78:79], v[16:17], 0, vcc
	global_load_dwordx4 v[28:31], v[16:17], off offset:16
	global_load_dwordx4 v[44:47], v[16:17], off
	global_load_dwordx4 v[48:51], v[18:19], off
	global_load_dwordx4 v[36:39], v[12:13], off offset:16
	s_nop 0
	global_load_dwordx4 v[12:15], v[16:17], off offset:144
	global_load_dwordx4 v[20:23], v[16:17], off offset:128
	global_load_dwordx4 v[24:27], v[18:19], off offset:128
	s_nop 0
	global_load_dwordx4 v[16:19], v[78:79], off offset:16
	s_waitcnt vmcnt(17)
	v_cvt_f32_f16_e32 v78, v56
	v_cvt_f32_f16_sdwa v79, v56 dst_sel:DWORD dst_unused:UNUSED_PAD src0_sel:WORD_1
	s_waitcnt vmcnt(16)
; #define LAS __attribute__((address_space(3)))
; template <bool ZETA>
; __device__ __forceinline__ void ret_stage(const Params& p, LAS unsigned char* lds, int tb, int h, int c, float logg, int tid) {
;     ...
;     for (int i = 0; i < 2; ++i) { const int id = tid + 512 * i, pos = id >> 3, ch = id & 7;
;         const half_t* src = PR + (size_t)(tb + pos) * NIN + C_RK + h * 128 + ch * 8;
;         const h8 x1 = *(const h8*)src, x2 = *(const h8*)(src + 64);
;         const float* cp = rot + (size_t)(c * 128 + pos) * 64 + ch * 8; const float* sp = cp + SEQ * 64;
;         const f32x4 c0 = *(const f32x4*)cp, c1 = *(const f32x4*)(cp + 4), s0 = *(const f32x4*)sp, s1 = *(const f32x4*)(sp + 4);
;         float sc = 0.08838834764831845f; if (ZETA) sc *= __expf(logg * (float)(127 - pos));
;         h8 y1, y2;
; #pragma unroll
;         for (int e = 0; e < 8; ++e) { const float co = e < 4 ? c0[e & 3] : c1[e & 3], si = e < 4 ? s0[e & 3] : s1[e & 3]; const float a = (float)x1[e], b = (float)x2[e];
;             y1[e] = (half_t)((a * co - b * si) * sc); y2[e] = (half_t)((b * co + a * si) * sc); }
;         *(LAS h8*)(Ks + pos * KSTR + ch * 8) = y1; *(LAS h8*)(Ks + pos * KSTR + 64 + ch * 8) = y2; }
; #pragma unroll
;     for (int i = 0; i < 8; ++i) { const int id = tid + 512 * i, pos = id >> 5, ch = id & 31;
;         *(LAS h8*)(Vs + pos * VSTR + ch * 8) = *(const h8*)(PR + (size_t)(tb + pos) * NIN + C_RV + h * 256 + ch * 8); }
	v_cvt_f32_f16_e32 v80, v52
	v_cvt_f32_f16_sdwa v81, v52 dst_sel:DWORD dst_unused:UNUSED_PAD src0_sel:WORD_1
	s_mov_b32 s60, 0x33800000
	v_cmp_gt_f32_e32 vcc, s60, v82
	v_cvt_f32_f16_e32 v86, v58
	v_cvt_f32_f16_sdwa v87, v58 dst_sel:DWORD dst_unused:UNUSED_PAD src0_sel:WORD_1
	v_cndmask_b32_e64 v97, v83, -v82, vcc
	s_waitcnt vmcnt(15)
	v_pk_mul_f32 v[82:83], v[70:71], v[78:79]
	v_pk_mul_f32 v[70:71], v[70:71], v[80:81]
	s_waitcnt vmcnt(13)
	v_pk_fma_f32 v[82:83], v[74:75], v[80:81], v[82:83]
	v_pk_fma_f32 v[70:71], v[74:75], v[78:79], v[70:71] neg_lo:[0,0,1] neg_hi:[0,0,1]
	v_cvt_f32_f16_e32 v74, v57
	v_cvt_f32_f16_sdwa v75, v57 dst_sel:DWORD dst_unused:UNUSED_PAD src0_sel:WORD_1
	v_cvt_f32_f16_e32 v78, v53
	v_cvt_f32_f16_sdwa v79, v53 dst_sel:DWORD dst_unused:UNUSED_PAD src0_sel:WORD_1
	v_pk_mul_f32 v[56:57], v[70:71], s[34:35] op_sel_hi:[1,0]
	v_pk_mul_f32 v[70:71], v[72:73], v[74:75]
	v_cvt_f32_f16_e32 v222, v54
	v_pk_fma_f32 v[70:71], v[76:77], v[78:79], v[70:71]
	v_cvt_f32_f16_sdwa v223, v54 dst_sel:DWORD dst_unused:UNUSED_PAD src0_sel:WORD_1
	v_pk_mul_f32 v[70:71], v[70:71], s[34:35] op_sel_hi:[1,0]
	v_cvt_pk_f16_f32 v56, v56, v57
	v_cvt_pk_f16_f32 v53, v70, v71
	v_pk_mul_f32 v[70:71], v[72:73], v[78:79]
	v_add_u32_e32 v58, s9, v127
	v_pk_fma_f32 v[70:71], v[76:77], v[74:75], v[70:71] neg_lo:[0,0,1] neg_hi:[0,0,1]
	v_add_u32_e32 v78, s49, v127
	v_pk_mul_f32 v[70:71], v[70:71], s[34:35] op_sel_hi:[1,0]
	v_ashrrev_i32_e32 v79, 31, v78
	v_cvt_pk_f16_f32 v57, v70, v71
	s_waitcnt vmcnt(12)
	v_pk_mul_f32 v[70:71], v[64:65], v[86:87]
	v_lshlrev_b64 v[78:79], 8, v[78:79]
	v_pk_fma_f32 v[70:71], v[60:61], v[222:223], v[70:71]
	v_pk_mul_f32 v[82:83], v[82:83], s[34:35] op_sel_hi:[1,0]
	v_pk_mul_f32 v[70:71], v[70:71], s[34:35] op_sel_hi:[1,0]
	v_lshl_add_u64 v[100:101], v[88:89], 0, v[78:79]
	v_cvt_pk_f16_f32 v54, v70, v71
	v_mad_i64_i32 v[70:71], vcc, v58, s35, v[68:69]
	v_lshl_add_u64 v[70:71], v[70:71], 0, s[20:21]
	v_lshl_add_u64 v[74:75], v[70:71], 0, v[92:93]
	v_cvt_pk_f16_f32 v52, v82, v83
	global_load_dwordx4 v[70:73], v[74:75], off offset:2048
	s_nop 0
	global_load_dwordx4 v[74:77], v[74:75], off offset:2176
	v_lshl_add_u64 v[104:105], v[100:101], 0, s[54:55]
	global_load_dwordx4 v[78:81], v[100:101], off offset:16
	global_load_dwordx4 v[82:85], v[100:101], off
	v_add_co_u32_e32 v100, vcc, s52, v100
	v_add_u32_e32 v58, s9, v129
	s_nop 0
	v_addc_co_u32_e32 v101, vcc, 0, v101, vcc
	v_mad_i64_i32 v[108:109], vcc, v58, s35, v[68:69]
	s_lshl_b32 s48, s48, 9
	s_mov_b32 s49, s21
	v_lshl_add_u64 v[108:109], v[108:109], 0, s[48:49]
	v_mov_b32_e32 v95, v3
	v_lshl_add_u64 v[108:109], v[108:109], 0, v[94:95]
	v_add_co_u32_e32 v108, vcc, s33, v108
	v_add_u32_e32 v58, s9, v130
	s_nop 0
	v_addc_co_u32_e32 v109, vcc, 0, v109, vcc
	v_mad_i64_i32 v[110:111], vcc, v58, s35, v[68:69]
	v_lshl_add_u64 v[110:111], v[110:111], 0, s[48:49]
	v_lshl_add_u64 v[110:111], v[110:111], 0, v[94:95]
	v_add_co_u32_e32 v112, vcc, s33, v110
	v_add_u32_e32 v58, s9, v131
	s_nop 0
	v_addc_co_u32_e32 v113, vcc, 0, v111, vcc
	v_mad_i64_i32 v[116:117], vcc, v58, s35, v[68:69]
	v_lshl_add_u64 v[116:117], v[116:117], 0, s[48:49]
	v_lshl_add_u64 v[116:117], v[116:117], 0, v[94:95]
	v_add_co_u32_e32 v116, vcc, s33, v116
	v_add_u32_e32 v58, s9, v132
	s_nop 0
	v_addc_co_u32_e32 v117, vcc, 0, v117, vcc
	v_mad_i64_i32 v[118:119], vcc, v58, s35, v[68:69]
	v_lshl_add_u64 v[118:119], v[118:119], 0, s[48:49]
	v_lshl_add_u64 v[118:119], v[118:119], 0, v[94:95]
	v_add_co_u32_e32 v120, vcc, s33, v118
	v_add_u32_e32 v58, s9, v133
	global_load_dwordx4 v[100:103], v[100:101], off
	s_nop 0
	global_load_dwordx4 v[104:107], v[104:105], off offset:16
	v_addc_co_u32_e32 v121, vcc, 0, v119, vcc
	v_mad_i64_i32 v[206:207], vcc, v58, s35, v[68:69]
	v_lshl_add_u64 v[206:207], v[206:207], 0, s[48:49]
	v_lshl_add_u64 v[206:207], v[206:207], 0, v[94:95]
	v_add_co_u32_e32 v206, vcc, s33, v206
	v_add_u32_e32 v58, s9, v134
	s_nop 0
	v_addc_co_u32_e32 v207, vcc, 0, v207, vcc
	v_mad_i64_i32 v[208:209], vcc, v58, s35, v[68:69]
	v_lshl_add_u64 v[208:209], v[208:209], 0, s[48:49]
	v_lshl_add_u64 v[208:209], v[208:209], 0, v[94:95]
	v_add_co_u32_e32 v210, vcc, s33, v208
	global_load_dwordx4 v[108:111], v[108:109], off
	s_nop 0
	global_load_dwordx4 v[112:115], v[112:113], off
	v_addc_co_u32_e32 v211, vcc, 0, v209, vcc
	global_load_dwordx4 v[116:119], v[116:117], off
	s_nop 0
	global_load_dwordx4 v[120:123], v[120:121], off
	s_nop 0
	global_load_dwordx4 v[206:209], v[206:207], off
	s_nop 0
	global_load_dwordx4 v[210:213], v[210:211], off
	v_add_u32_e32 v58, s9, v135
	v_mad_i64_i32 v[214:215], vcc, v58, s35, v[68:69]
	v_lshl_add_u64 v[214:215], v[214:215], 0, s[48:49]
	v_lshl_add_u64 v[214:215], v[214:215], 0, v[94:95]
	v_add_co_u32_e32 v214, vcc, s33, v214
	v_add_u32_e32 v58, s9, v136
	s_nop 0
	v_addc_co_u32_e32 v215, vcc, 0, v215, vcc
	v_mad_i64_i32 v[68:69], vcc, v58, s35, v[68:69]
	v_lshl_add_u64 v[68:69], v[68:69], 0, s[48:49]
	v_lshl_add_u64 v[68:69], v[68:69], 0, v[94:95]
	v_add_co_u32_e32 v68, vcc, s33, v68
	v_pk_mul_f32 v[64:65], v[64:65], v[222:223]
	s_nop 0
	v_addc_co_u32_e32 v69, vcc, 0, v69, vcc
	global_load_dwordx4 v[214:217], v[214:215], off
	s_nop 0
	global_load_dwordx4 v[218:221], v[68:69], off
	v_pk_fma_f32 v[60:61], v[60:61], v[86:87], v[64:65] neg_lo:[0,0,1] neg_hi:[0,0,1]
	v_cvt_f32_f16_e32 v64, v59
	v_cvt_f32_f16_sdwa v65, v59 dst_sel:DWORD dst_unused:UNUSED_PAD src0_sel:WORD_1
	v_cvt_f32_f16_e32 v68, v55
	v_cvt_f32_f16_sdwa v69, v55 dst_sel:DWORD dst_unused:UNUSED_PAD src0_sel:WORD_1
	v_pk_mul_f32 v[58:59], v[60:61], s[34:35] op_sel_hi:[1,0]
	v_pk_mul_f32 v[60:61], v[66:67], v[64:65]
	v_cvt_pk_f16_f32 v58, v58, v59
	v_pk_fma_f32 v[60:61], v[62:63], v[68:69], v[60:61]
	s_cmp_eq_u32 s8, 0
	v_pk_mul_f32 v[60:61], v[60:61], s[34:35] op_sel_hi:[1,0]
	s_nop 0
	v_cvt_pk_f16_f32 v55, v60, v61
	v_pk_mul_f32 v[60:61], v[66:67], v[68:69]
	s_waitcnt vmcnt(12)
; #define LAS __attribute__((address_space(3)))
; template <bool ZETA>
; __device__ __forceinline__ void ret_stage(const Params& p, LAS unsigned char* lds, int tb, int h, int c, float logg, int tid) {
;     ...
;         for (int e = 0; e < 8; ++e) { const float co = e < 4 ? c0[e & 3] : c1[e & 3], si = e < 4 ? s0[e & 3] : s1[e & 3]; const float a = (float)x1[e], b = (float)x2[e];
;             y1[e] = (half_t)((a * co - b * si) * sc); y2[e] = (half_t)((b * co + a * si) * sc); }
;         *(LAS h8*)(Ks + pos * KSTR + ch * 8) = y1; *(LAS h8*)(Ks + pos * KSTR + 64 + ch * 8) = y2; }
; #pragma unroll
;     for (int i = 0; i < 8; ++i) { const int id = tid + 512 * i, pos = id >> 5, ch = id & 31;
;         *(LAS h8*)(Vs + pos * VSTR + ch * 8) = *(const h8*)(PR + (size_t)(tb + pos) * NIN + C_RV + h * 256 + ch * 8); }
; __device__ __forceinline__ void ret_out_item(const Params& p, int l, LAS unsigned char* lds, int item, int tid, int wave, int lane) {
;     ...
;     { const float xi = __expf(logg * (float)(nq + 1));
; #pragma unroll
;       for (int ks = 0; ks < 2; ++ks) {
; #pragma unroll
;           for (int e = 0; e < 8; ++e) { const float co = e < 4 ? rc[ks][0][e & 3] : rc[ks][1][e & 3], si = e < 4 ? rs[ks][0][e & 3] : rs[ks][1][e & 3]; const float a = (float)xq[ks][e], bb = (float)xq[ks + 2][e];
;               const float y1 = a * co - bb * si, y2 = bb * co + a * si;
;               qf[ks][e] = (half_t)y1; qf[ks + 2][e] = (half_t)y2; qx[ks][e] = (half_t)(y1 * xi); qx[ks + 2][e] = (half_t)(y2 * xi); } } }
;     f32x4 o[16];
; #pragma unroll
;     for (int i = 0; i < 16; ++i) o[i] = (f32x4){0.f, 0.f, 0.f, 0.f};
;     if (c > 0) {
	v_cvt_f32_f16_e32 v66, v76
	v_pk_fma_f32 v[60:61], v[62:63], v[64:65], v[60:61] neg_lo:[0,0,1] neg_hi:[0,0,1]
	v_cvt_f32_f16_e32 v62, v70
	v_pk_mul_f32 v[60:61], v[60:61], s[34:35] op_sel_hi:[1,0]
	v_cvt_f32_f16_sdwa v63, v70 dst_sel:DWORD dst_unused:UNUSED_PAD src0_sel:WORD_1
	v_cvt_pk_f16_f32 v59, v60, v61
	v_cvt_f32_f16_e32 v60, v74
	v_cvt_f32_f16_sdwa v61, v74 dst_sel:DWORD dst_unused:UNUSED_PAD src0_sel:WORD_1
	v_cvt_f32_f16_e32 v64, v71
	v_cvt_f32_f16_sdwa v65, v71 dst_sel:DWORD dst_unused:UNUSED_PAD src0_sel:WORD_1
	ds_write_b128 v126, v[56:59]
	ds_write_b128 v126, v[52:55] offset:128
	v_cvt_f32_f16_e32 v58, v75
	v_cvt_f32_f16_sdwa v59, v75 dst_sel:DWORD dst_unused:UNUSED_PAD src0_sel:WORD_1
	v_cvt_f32_f16_e32 v68, v72
	v_cvt_f32_f16_sdwa v69, v72 dst_sel:DWORD dst_unused:UNUSED_PAD src0_sel:WORD_1
	v_cvt_f32_f16_sdwa v67, v76 dst_sel:DWORD dst_unused:UNUSED_PAD src0_sel:WORD_1
	s_waitcnt vmcnt(9)
	v_pk_mul_f32 v[52:53], v[100:101], v[62:63]
	s_nop 0
	v_pk_fma_f32 v[52:53], v[82:83], v[60:61], v[52:53]
	v_pk_mul_f32 v[56:57], v[100:101], v[60:61]
	v_cvt_f32_f16_e32 v60, v73
	v_cvt_f32_f16_sdwa v61, v73 dst_sel:DWORD dst_unused:UNUSED_PAD src0_sel:WORD_1
	v_pk_mul_f32 v[54:55], v[102:103], v[64:65]
	v_pk_fma_f32 v[56:57], v[82:83], v[62:63], v[56:57] neg_lo:[0,0,1] neg_hi:[0,0,1]
	v_cvt_f32_f16_e32 v62, v77
	v_cvt_f32_f16_sdwa v63, v77 dst_sel:DWORD dst_unused:UNUSED_PAD src0_sel:WORD_1
	v_pk_fma_f32 v[54:55], v[84:85], v[58:59], v[54:55]
	v_pk_mul_f32 v[58:59], v[102:103], v[58:59]
	v_pk_mul_f32 v[52:53], v[52:53], s[34:35] op_sel_hi:[1,0]
	v_pk_fma_f32 v[58:59], v[84:85], v[64:65], v[58:59] neg_lo:[0,0,1] neg_hi:[0,0,1]
	v_pk_mul_f32 v[54:55], v[54:55], s[34:35] op_sel_hi:[1,0]
	v_pk_mul_f32 v[56:57], v[56:57], s[34:35] op_sel_hi:[1,0]
	v_pk_mul_f32 v[58:59], v[58:59], s[34:35] op_sel_hi:[1,0]
	s_waitcnt vmcnt(8)
	v_pk_mul_f32 v[64:65], v[106:107], v[60:61]
	v_cvt_pk_f16_f32 v52, v52, v53
	v_cvt_pk_f16_f32 v53, v54, v55
	v_pk_mul_f32 v[54:55], v[104:105], v[68:69]
	v_cvt_pk_f16_f32 v56, v56, v57
	v_cvt_pk_f16_f32 v57, v58, v59
	v_pk_mul_f32 v[58:59], v[104:105], v[66:67]
	v_pk_fma_f32 v[64:65], v[80:81], v[62:63], v[64:65]
	v_pk_mul_f32 v[62:63], v[106:107], v[62:63]
	v_pk_fma_f32 v[54:55], v[78:79], v[66:67], v[54:55]
	v_pk_fma_f32 v[58:59], v[78:79], v[68:69], v[58:59] neg_lo:[0,0,1] neg_hi:[0,0,1]
	v_pk_fma_f32 v[60:61], v[80:81], v[60:61], v[62:63] neg_lo:[0,0,1] neg_hi:[0,0,1]
	v_pk_mul_f32 v[54:55], v[54:55], s[34:35] op_sel_hi:[1,0]
	v_pk_mul_f32 v[58:59], v[58:59], s[34:35] op_sel_hi:[1,0]
	v_pk_mul_f32 v[64:65], v[64:65], s[34:35] op_sel_hi:[1,0]
	v_pk_mul_f32 v[60:61], v[60:61], s[34:35] op_sel_hi:[1,0]
	v_cvt_pk_f16_f32 v54, v54, v55
	v_cvt_pk_f16_f32 v58, v58, v59
	v_cvt_pk_f16_f32 v55, v64, v65
	v_cvt_pk_f16_f32 v59, v60, v61
	ds_write_b128 v128, v[56:59]
	ds_write_b128 v128, v[52:55] offset:128
	s_waitcnt vmcnt(7)
	ds_write_b128 v198, v[108:111] offset:34816
	s_waitcnt vmcnt(6)
	ds_write_b128 v199, v[112:115] offset:34816
	s_waitcnt vmcnt(5)
	ds_write_b128 v200, v[116:119] offset:34816
	s_waitcnt vmcnt(4)
	ds_write_b128 v201, v[120:123] offset:34816
	s_waitcnt vmcnt(3)
	ds_write_b128 v202, v[206:209] offset:34816
	s_waitcnt vmcnt(2)
	ds_write_b128 v203, v[210:213] offset:34816
	v_cvt_f32_f16_e32 v52, v40
	v_cvt_f32_f16_sdwa v53, v40 dst_sel:DWORD dst_unused:UNUSED_PAD src0_sel:WORD_1
	v_cvt_f32_f16_e32 v54, v32
	v_cvt_f32_f16_sdwa v55, v32 dst_sel:DWORD dst_unused:UNUSED_PAD src0_sel:WORD_1
	v_cvt_f32_f16_e32 v40, v41
	v_cvt_f32_f16_sdwa v41, v41 dst_sel:DWORD dst_unused:UNUSED_PAD src0_sel:WORD_1
	v_cvt_f32_f16_e32 v32, v33
	v_cvt_f32_f16_sdwa v33, v33 dst_sel:DWORD dst_unused:UNUSED_PAD src0_sel:WORD_1
	v_pk_mul_f32 v[56:57], v[48:49], v[52:53]
	v_pk_mul_f32 v[48:49], v[48:49], v[54:55]
	v_pk_fma_f32 v[84:85], v[44:45], v[54:55], v[56:57] neg_lo:[0,0,1] neg_hi:[0,0,1]
	v_pk_fma_f32 v[86:87], v[44:45], v[52:53], v[48:49]
	v_pk_mul_f32 v[44:45], v[50:51], v[40:41]
	v_cvt_f32_f16_e32 v48, v34
	v_pk_fma_f32 v[80:81], v[46:47], v[32:33], v[44:45] neg_lo:[0,0,1] neg_hi:[0,0,1]
	v_cvt_f32_f16_e32 v44, v42
	v_cvt_f32_f16_sdwa v45, v42 dst_sel:DWORD dst_unused:UNUSED_PAD src0_sel:WORD_1
	v_cvt_f32_f16_sdwa v49, v34 dst_sel:DWORD dst_unused:UNUSED_PAD src0_sel:WORD_1
	v_pk_mul_f32 v[32:33], v[50:51], v[32:33]
	v_cvt_f32_f16_e32 v34, v35
	v_pk_fma_f32 v[100:101], v[46:47], v[40:41], v[32:33]
	v_pk_mul_f32 v[32:33], v[36:37], v[44:45]
	v_cvt_f32_f16_sdwa v35, v35 dst_sel:DWORD dst_unused:UNUSED_PAD src0_sel:WORD_1
	v_pk_fma_f32 v[102:103], v[28:29], v[48:49], v[32:33] neg_lo:[0,0,1] neg_hi:[0,0,1]
	v_cvt_f32_f16_e32 v32, v43
	v_cvt_f32_f16_sdwa v33, v43 dst_sel:DWORD dst_unused:UNUSED_PAD src0_sel:WORD_1
	v_pk_mul_f32 v[36:37], v[36:37], v[48:49]
	s_waitcnt vmcnt(1)
	ds_write_b128 v204, v[214:217] offset:34816
	s_waitcnt vmcnt(0)
	ds_write_b128 v205, v[218:221] offset:34816
	v_pk_fma_f32 v[104:105], v[28:29], v[44:45], v[36:37]
	v_pk_mul_f32 v[28:29], v[38:39], v[32:33]
	v_cvt_f32_f16_e32 v36, v4
	v_pk_fma_f32 v[82:83], v[30:31], v[34:35], v[28:29] neg_lo:[0,0,1] neg_hi:[0,0,1]
	v_cvt_f32_f16_e32 v28, v8
	v_cvt_f32_f16_sdwa v29, v8 dst_sel:DWORD dst_unused:UNUSED_PAD src0_sel:WORD_1
	v_cvt_f32_f16_sdwa v37, v4 dst_sel:DWORD dst_unused:UNUSED_PAD src0_sel:WORD_1
	v_cvt_f32_f16_e32 v8, v9
	v_cvt_f32_f16_sdwa v9, v9 dst_sel:DWORD dst_unused:UNUSED_PAD src0_sel:WORD_1
	v_cvt_f32_f16_e32 v4, v5
	v_cvt_f32_f16_sdwa v5, v5 dst_sel:DWORD dst_unused:UNUSED_PAD src0_sel:WORD_1
	v_pk_mul_f32 v[34:35], v[38:39], v[34:35]
	s_nop 0
	v_pk_fma_f32 v[110:111], v[30:31], v[32:33], v[34:35]
	v_pk_mul_f32 v[30:31], v[24:25], v[28:29]
	v_pk_mul_f32 v[24:25], v[24:25], v[36:37]
	v_pk_fma_f32 v[106:107], v[20:21], v[36:37], v[30:31] neg_lo:[0,0,1] neg_hi:[0,0,1]
	v_pk_fma_f32 v[108:109], v[20:21], v[28:29], v[24:25]
	v_pk_mul_f32 v[20:21], v[26:27], v[8:9]
	v_cvt_f32_f16_e32 v24, v6
	v_pk_fma_f32 v[112:113], v[22:23], v[4:5], v[20:21] neg_lo:[0,0,1] neg_hi:[0,0,1]
	v_cvt_f32_f16_e32 v20, v10
	v_cvt_f32_f16_sdwa v21, v10 dst_sel:DWORD dst_unused:UNUSED_PAD src0_sel:WORD_1
	v_cvt_f32_f16_sdwa v25, v6 dst_sel:DWORD dst_unused:UNUSED_PAD src0_sel:WORD_1
	v_pk_mul_f32 v[4:5], v[26:27], v[4:5]
	v_cvt_f32_f16_e32 v6, v7
	v_pk_fma_f32 v[114:115], v[22:23], v[8:9], v[4:5]
	v_pk_mul_f32 v[4:5], v[16:17], v[20:21]
	v_cvt_f32_f16_sdwa v7, v7 dst_sel:DWORD dst_unused:UNUSED_PAD src0_sel:WORD_1
	v_pk_fma_f32 v[116:117], v[12:13], v[24:25], v[4:5] neg_lo:[0,0,1] neg_hi:[0,0,1]
	v_cvt_f32_f16_e32 v4, v11
	v_cvt_f32_f16_sdwa v5, v11 dst_sel:DWORD dst_unused:UNUSED_PAD src0_sel:WORD_1
	v_pk_mul_f32 v[8:9], v[16:17], v[24:25]
	s_nop 0
	v_pk_fma_f32 v[118:119], v[12:13], v[20:21], v[8:9]
	v_pk_mul_f32 v[8:9], v[18:19], v[4:5]
	s_nop 0
	v_pk_fma_f32 v[122:123], v[14:15], v[6:7], v[8:9] neg_lo:[0,0,1] neg_hi:[0,0,1]
	v_pk_mul_f32 v[6:7], v[18:19], v[6:7]
	s_nop 0
	v_pk_fma_f32 v[120:121], v[14:15], v[4:5], v[6:7]
	s_cbranch_scc1 .LBB0_525
; __device__ __forceinline__ void ret_out_item(const Params& p, int l, LAS unsigned char* lds, int item, int tid, int wave, int lane) {
;     ...
;     { const float xi = __expf(logg * (float)(nq + 1));
; #pragma unroll
;       for (int ks = 0; ks < 2; ++ks) {
; #pragma unroll
;           for (int e = 0; e < 8; ++e) { const float co = e < 4 ? rc[ks][0][e & 3] : rc[ks][1][e & 3], si = e < 4 ? rs[ks][0][e & 3] : rs[ks][1][e & 3]; const float a = (float)xq[ks][e], bb = (float)xq[ks + 2][e];
;               const float y1 = a * co - bb * si, y2 = bb * co + a * si;
;               qf[ks][e] = (half_t)y1; qf[ks + 2][e] = (half_t)y2; qx[ks][e] = (half_t)(y1 * xi); qx[ks + 2][e] = (half_t)(y2 * xi); } } }
;     f32x4 o[16];
; #pragma unroll
;     for (int i = 0; i < 16; ++i) o[i] = (f32x4){0.f, 0.f, 0.f, 0.f};
;     if (c > 0) {
;         const half_t* Sp = (const half_t*)(p.ws + WS_ST) + (size_t)item * 32768;
; #pragma unroll
;         for (int dvt = 0; dvt < 16; ++dvt) {
; #pragma unroll
;             for (int ks = 0; ks < 4; ++ks) { const h8 af = *(const h8*)(Sp + (size_t)(((dvt * 4 + ks) * 64 + lane) * 8));
;                 o[dvt] = __builtin_amdgcn_mfma_f32_16x16x32_f16(af, qx[ks], o[dvt], 0, 0, 0); } }
	v_mul_f32_e32 v4, v97, v137
	v_mul_f32_e32 v4, 0x3fb8aa3b, v4
	v_exp_f32_e32 v8, v4
	v_add_co_u32_e32 v16, vcc, s33, v90
	s_movk_i32 s8, 0x2000
	v_pk_mul_f32 v[10:11], v[8:9], v[106:107] op_sel_hi:[0,1]
	v_cvt_pk_f16_f32 v72, v10, v11
	v_pk_mul_f32 v[10:11], v[8:9], v[112:113] op_sel_hi:[0,1]
	v_cvt_pk_f16_f32 v73, v10, v11
	v_pk_mul_f32 v[10:11], v[8:9], v[116:117] op_sel_hi:[0,1]
	v_cvt_pk_f16_f32 v74, v10, v11
	v_pk_mul_f32 v[10:11], v[8:9], v[86:87] op_sel_hi:[0,1]
	v_cvt_pk_f16_f32 v68, v10, v11
	v_pk_mul_f32 v[10:11], v[8:9], v[100:101] op_sel_hi:[0,1]
	v_cvt_pk_f16_f32 v69, v10, v11
	v_pk_mul_f32 v[10:11], v[8:9], v[104:105] op_sel_hi:[0,1]
	v_cvt_pk_f16_f32 v70, v10, v11
	v_pk_mul_f32 v[10:11], v[8:9], v[110:111] op_sel_hi:[0,1]
	v_cvt_pk_f16_f32 v71, v10, v11
	v_pk_mul_f32 v[10:11], v[8:9], v[84:85] op_sel_hi:[0,1]
	v_cvt_pk_f16_f32 v76, v10, v11
	v_pk_mul_f32 v[10:11], v[8:9], v[80:81] op_sel_hi:[0,1]
	v_cvt_pk_f16_f32 v77, v10, v11
	v_pk_mul_f32 v[10:11], v[8:9], v[102:103] op_sel_hi:[0,1]
	v_pk_mul_f32 v[4:5], v[8:9], v[108:109] op_sel_hi:[0,1]
	v_pk_mul_f32 v[6:7], v[8:9], v[114:115] op_sel_hi:[0,1]
	v_cvt_pk_f16_f32 v78, v10, v11
	v_pk_mul_f32 v[10:11], v[8:9], v[82:83] op_sel_hi:[0,1]
	v_cvt_pk_f16_f32 v4, v4, v5
	v_cvt_pk_f16_f32 v5, v6, v7
	v_pk_mul_f32 v[6:7], v[8:9], v[118:119] op_sel_hi:[0,1]
	v_cvt_pk_f16_f32 v79, v10, v11
	v_pk_mul_f32 v[10:11], v[8:9], v[120:121] op_sel_hi:[0,1]
	v_pk_mul_f32 v[8:9], v[8:9], v[122:123] op_sel_hi:[0,1]
	v_cvt_pk_f16_f32 v6, v6, v7
	v_cvt_pk_f16_f32 v7, v10, v11
	v_cvt_pk_f16_f32 v75, v8, v9
	v_add_co_u32_e32 v248, vcc, 0x1000, v90
	s_nop 1
	v_addc_co_u32_e32 v249, vcc, 0, v91, vcc
	global_load_dwordx4 v[212:215], v[248:249], off offset:-4096
	global_load_dwordx4 v[216:219], v[248:249], off offset:-3072
	global_load_dwordx4 v[220:223], v[248:249], off offset:-2048
	global_load_dwordx4 v[224:227], v[248:249], off offset:-1024
	global_load_dwordx4 v[228:231], v[248:249], off
	global_load_dwordx4 v[232:235], v[248:249], off offset:1024
	global_load_dwordx4 v[236:239], v[248:249], off offset:2048
	global_load_dwordx4 v[240:243], v[248:249], off offset:3072
	v_add_co_u32_e32 v248, vcc, 0x2000, v248
	s_nop 1
	v_addc_co_u32_e32 v249, vcc, 0, v249, vcc
	s_waitcnt vmcnt(7)
	v_mfma_f32_16x16x32_f16 v[208:211], v[212:215], v[76:79], 0
	global_load_dwordx4 v[212:215], v[248:249], off offset:-4096
	s_waitcnt vmcnt(7)
	v_mfma_f32_16x16x32_f16 v[208:211], v[216:219], v[72:75], v[208:211]
	global_load_dwordx4 v[216:219], v[248:249], off offset:-3072
	s_waitcnt vmcnt(7)
	v_mfma_f32_16x16x32_f16 v[208:211], v[220:223], v[68:71], v[208:211]
	global_load_dwordx4 v[220:223], v[248:249], off offset:-2048
	s_waitcnt vmcnt(7)
	v_mfma_f32_16x16x32_f16 v[64:67], v[224:227], v[4:7], v[208:211]
	global_load_dwordx4 v[224:227], v[248:249], off offset:-1024
	s_waitcnt vmcnt(7)
	v_mfma_f32_16x16x32_f16 v[244:247], v[228:231], v[76:79], 0
	global_load_dwordx4 v[228:231], v[248:249], off
	s_waitcnt vmcnt(7)
	v_mfma_f32_16x16x32_f16 v[244:247], v[232:235], v[72:75], v[244:247]
	global_load_dwordx4 v[232:235], v[248:249], off offset:1024
	s_waitcnt vmcnt(7)
	v_mfma_f32_16x16x32_f16 v[244:247], v[236:239], v[68:71], v[244:247]
	global_load_dwordx4 v[236:239], v[248:249], off offset:2048
	s_waitcnt vmcnt(7)
	v_mfma_f32_16x16x32_f16 v[60:63], v[240:243], v[4:7], v[244:247]
	global_load_dwordx4 v[240:243], v[248:249], off offset:3072
	v_add_co_u32_e32 v248, vcc, 0x2000, v248
	s_nop 1
	v_addc_co_u32_e32 v249, vcc, 0, v249, vcc
	s_waitcnt vmcnt(7)
	v_mfma_f32_16x16x32_f16 v[208:211], v[212:215], v[76:79], 0
	global_load_dwordx4 v[212:215], v[248:249], off offset:-4096
	s_waitcnt vmcnt(7)
	v_mfma_f32_16x16x32_f16 v[208:211], v[216:219], v[72:75], v[208:211]
	global_load_dwordx4 v[216:219], v[248:249], off offset:-3072
	s_waitcnt vmcnt(7)
	v_mfma_f32_16x16x32_f16 v[208:211], v[220:223], v[68:71], v[208:211]
	global_load_dwordx4 v[220:223], v[248:249], off offset:-2048
	s_waitcnt vmcnt(7)
	v_mfma_f32_16x16x32_f16 v[44:47], v[224:227], v[4:7], v[208:211]
	global_load_dwordx4 v[224:227], v[248:249], off offset:-1024
	s_waitcnt vmcnt(7)
	v_mfma_f32_16x16x32_f16 v[244:247], v[228:231], v[76:79], 0
	global_load_dwordx4 v[228:231], v[248:249], off
	s_waitcnt vmcnt(7)
	v_mfma_f32_16x16x32_f16 v[244:247], v[232:235], v[72:75], v[244:247]
	global_load_dwordx4 v[232:235], v[248:249], off offset:1024
	s_waitcnt vmcnt(7)
	v_mfma_f32_16x16x32_f16 v[244:247], v[236:239], v[68:71], v[244:247]
	global_load_dwordx4 v[236:239], v[248:249], off offset:2048
	s_waitcnt vmcnt(7)
	v_mfma_f32_16x16x32_f16 v[48:51], v[240:243], v[4:7], v[244:247]
	global_load_dwordx4 v[240:243], v[248:249], off offset:3072
	v_add_co_u32_e32 v248, vcc, 0x2000, v248
	s_nop 1
	v_addc_co_u32_e32 v249, vcc, 0, v249, vcc
	s_waitcnt vmcnt(7)
	v_mfma_f32_16x16x32_f16 v[208:211], v[212:215], v[76:79], 0
	global_load_dwordx4 v[212:215], v[248:249], off offset:-4096
	s_waitcnt vmcnt(7)
	v_mfma_f32_16x16x32_f16 v[208:211], v[216:219], v[72:75], v[208:211]
	global_load_dwordx4 v[216:219], v[248:249], off offset:-3072
	s_waitcnt vmcnt(7)
	v_mfma_f32_16x16x32_f16 v[208:211], v[220:223], v[68:71], v[208:211]
	global_load_dwordx4 v[220:223], v[248:249], off offset:-2048
	s_waitcnt vmcnt(7)
	v_mfma_f32_16x16x32_f16 v[56:59], v[224:227], v[4:7], v[208:211]
	global_load_dwordx4 v[224:227], v[248:249], off offset:-1024
	s_waitcnt vmcnt(7)
	v_mfma_f32_16x16x32_f16 v[244:247], v[228:231], v[76:79], 0
	global_load_dwordx4 v[228:231], v[248:249], off
	s_waitcnt vmcnt(7)
	v_mfma_f32_16x16x32_f16 v[244:247], v[232:235], v[72:75], v[244:247]
	global_load_dwordx4 v[232:235], v[248:249], off offset:1024
	s_waitcnt vmcnt(7)
; __device__ __forceinline__ void ret_out_item(const Params& p, int l, LAS unsigned char* lds, int item, int tid, int wave, int lane) {
;     ...
;     if (c > 0) {
;         const half_t* Sp = (const half_t*)(p.ws + WS_ST) + (size_t)item * 32768;
; #pragma unroll
;         for (int dvt = 0; dvt < 16; ++dvt) {
; #pragma unroll
;             for (int ks = 0; ks < 4; ++ks) { const h8 af = *(const h8*)(Sp + (size_t)(((dvt * 4 + ks) * 64 + lane) * 8));
;                 o[dvt] = __builtin_amdgcn_mfma_f32_16x16x32_f16(af, qx[ks], o[dvt], 0, 0, 0); } }
	v_mfma_f32_16x16x32_f16 v[244:247], v[236:239], v[68:71], v[244:247]
	global_load_dwordx4 v[236:239], v[248:249], off offset:2048
	s_waitcnt vmcnt(7)
	v_mfma_f32_16x16x32_f16 v[52:55], v[240:243], v[4:7], v[244:247]
	global_load_dwordx4 v[240:243], v[248:249], off offset:3072
	v_add_co_u32_e32 v248, vcc, 0x2000, v248
	s_nop 1
	v_addc_co_u32_e32 v249, vcc, 0, v249, vcc
	s_waitcnt vmcnt(7)
	v_mfma_f32_16x16x32_f16 v[208:211], v[212:215], v[76:79], 0
	global_load_dwordx4 v[212:215], v[248:249], off offset:-4096
	s_waitcnt vmcnt(7)
	v_mfma_f32_16x16x32_f16 v[208:211], v[216:219], v[72:75], v[208:211]
	global_load_dwordx4 v[216:219], v[248:249], off offset:-3072
	s_waitcnt vmcnt(7)
	v_mfma_f32_16x16x32_f16 v[208:211], v[220:223], v[68:71], v[208:211]
	global_load_dwordx4 v[220:223], v[248:249], off offset:-2048
	s_waitcnt vmcnt(7)
	v_mfma_f32_16x16x32_f16 v[36:39], v[224:227], v[4:7], v[208:211]
	global_load_dwordx4 v[224:227], v[248:249], off offset:-1024
	s_waitcnt vmcnt(7)
	v_mfma_f32_16x16x32_f16 v[244:247], v[228:231], v[76:79], 0
	global_load_dwordx4 v[228:231], v[248:249], off
	s_waitcnt vmcnt(7)
	v_mfma_f32_16x16x32_f16 v[244:247], v[232:235], v[72:75], v[244:247]
	global_load_dwordx4 v[232:235], v[248:249], off offset:1024
	s_waitcnt vmcnt(7)
	v_mfma_f32_16x16x32_f16 v[244:247], v[236:239], v[68:71], v[244:247]
	global_load_dwordx4 v[236:239], v[248:249], off offset:2048
	s_waitcnt vmcnt(7)
	v_mfma_f32_16x16x32_f16 v[40:43], v[240:243], v[4:7], v[244:247]
	global_load_dwordx4 v[240:243], v[248:249], off offset:3072
	v_add_co_u32_e32 v248, vcc, 0x2000, v248
	s_nop 1
	v_addc_co_u32_e32 v249, vcc, 0, v249, vcc
	s_waitcnt vmcnt(7)
	v_mfma_f32_16x16x32_f16 v[208:211], v[212:215], v[76:79], 0
	global_load_dwordx4 v[212:215], v[248:249], off offset:-4096
	s_waitcnt vmcnt(7)
	v_mfma_f32_16x16x32_f16 v[208:211], v[216:219], v[72:75], v[208:211]
	global_load_dwordx4 v[216:219], v[248:249], off offset:-3072
	s_waitcnt vmcnt(7)
	v_mfma_f32_16x16x32_f16 v[208:211], v[220:223], v[68:71], v[208:211]
	global_load_dwordx4 v[220:223], v[248:249], off offset:-2048
	s_waitcnt vmcnt(7)
	v_mfma_f32_16x16x32_f16 v[32:35], v[224:227], v[4:7], v[208:211]
	global_load_dwordx4 v[224:227], v[248:249], off offset:-1024
	s_waitcnt vmcnt(7)
	v_mfma_f32_16x16x32_f16 v[244:247], v[228:231], v[76:79], 0
	global_load_dwordx4 v[228:231], v[248:249], off
	s_waitcnt vmcnt(7)
	v_mfma_f32_16x16x32_f16 v[244:247], v[232:235], v[72:75], v[244:247]
	global_load_dwordx4 v[232:235], v[248:249], off offset:1024
	s_waitcnt vmcnt(7)
	v_mfma_f32_16x16x32_f16 v[244:247], v[236:239], v[68:71], v[244:247]
	global_load_dwordx4 v[236:239], v[248:249], off offset:2048
	s_waitcnt vmcnt(7)
	v_mfma_f32_16x16x32_f16 v[28:31], v[240:243], v[4:7], v[244:247]
	global_load_dwordx4 v[240:243], v[248:249], off offset:3072
	v_add_co_u32_e32 v248, vcc, 0x2000, v248
	s_nop 1
	v_addc_co_u32_e32 v249, vcc, 0, v249, vcc
	s_waitcnt vmcnt(7)
	v_mfma_f32_16x16x32_f16 v[208:211], v[212:215], v[76:79], 0
	global_load_dwordx4 v[212:215], v[248:249], off offset:-4096
	s_waitcnt vmcnt(7)
	v_mfma_f32_16x16x32_f16 v[208:211], v[216:219], v[72:75], v[208:211]
	global_load_dwordx4 v[216:219], v[248:249], off offset:-3072
	s_waitcnt vmcnt(7)
	v_mfma_f32_16x16x32_f16 v[208:211], v[220:223], v[68:71], v[208:211]
	global_load_dwordx4 v[220:223], v[248:249], off offset:-2048
	s_waitcnt vmcnt(7)
	v_mfma_f32_16x16x32_f16 v[20:23], v[224:227], v[4:7], v[208:211]
	global_load_dwordx4 v[224:227], v[248:249], off offset:-1024
	s_waitcnt vmcnt(7)
	v_mfma_f32_16x16x32_f16 v[244:247], v[228:231], v[76:79], 0
	global_load_dwordx4 v[228:231], v[248:249], off
	s_waitcnt vmcnt(7)
	v_mfma_f32_16x16x32_f16 v[244:247], v[232:235], v[72:75], v[244:247]
	global_load_dwordx4 v[232:235], v[248:249], off offset:1024
	s_waitcnt vmcnt(7)
	v_mfma_f32_16x16x32_f16 v[244:247], v[236:239], v[68:71], v[244:247]
	global_load_dwordx4 v[236:239], v[248:249], off offset:2048
	s_waitcnt vmcnt(7)
	v_mfma_f32_16x16x32_f16 v[24:27], v[240:243], v[4:7], v[244:247]
	global_load_dwordx4 v[240:243], v[248:249], off offset:3072
	v_add_co_u32_e32 v248, vcc, 0x2000, v248
	s_nop 1
	v_addc_co_u32_e32 v249, vcc, 0, v249, vcc
	s_waitcnt vmcnt(7)
	v_mfma_f32_16x16x32_f16 v[208:211], v[212:215], v[76:79], 0
	global_load_dwordx4 v[212:215], v[248:249], off offset:-4096
	s_waitcnt vmcnt(7)
	v_mfma_f32_16x16x32_f16 v[208:211], v[216:219], v[72:75], v[208:211]
	global_load_dwordx4 v[216:219], v[248:249], off offset:-3072
	s_waitcnt vmcnt(7)
	v_mfma_f32_16x16x32_f16 v[208:211], v[220:223], v[68:71], v[208:211]
	global_load_dwordx4 v[220:223], v[248:249], off offset:-2048
	s_waitcnt vmcnt(7)
	v_mfma_f32_16x16x32_f16 v[16:19], v[224:227], v[4:7], v[208:211]
	global_load_dwordx4 v[224:227], v[248:249], off offset:-1024
	s_waitcnt vmcnt(7)
	v_mfma_f32_16x16x32_f16 v[244:247], v[228:231], v[76:79], 0
	global_load_dwordx4 v[228:231], v[248:249], off
	s_waitcnt vmcnt(7)
	v_mfma_f32_16x16x32_f16 v[244:247], v[232:235], v[72:75], v[244:247]
	global_load_dwordx4 v[232:235], v[248:249], off offset:1024
	s_waitcnt vmcnt(7)
	v_mfma_f32_16x16x32_f16 v[244:247], v[236:239], v[68:71], v[244:247]
	global_load_dwordx4 v[236:239], v[248:249], off offset:2048
	s_waitcnt vmcnt(7)
	v_mfma_f32_16x16x32_f16 v[12:15], v[240:243], v[4:7], v[244:247]
	global_load_dwordx4 v[240:243], v[248:249], off offset:3072
	s_waitcnt vmcnt(7)
	v_mfma_f32_16x16x32_f16 v[208:211], v[212:215], v[76:79], 0
	s_waitcnt vmcnt(6)
	v_mfma_f32_16x16x32_f16 v[208:211], v[216:219], v[72:75], v[208:211]
	s_waitcnt vmcnt(5)
	v_mfma_f32_16x16x32_f16 v[208:211], v[220:223], v[68:71], v[208:211]
	s_waitcnt vmcnt(4)
	v_mfma_f32_16x16x32_f16 v[8:11], v[224:227], v[4:7], v[208:211]
	s_waitcnt vmcnt(3)
	v_mfma_f32_16x16x32_f16 v[244:247], v[228:231], v[76:79], 0
	s_waitcnt vmcnt(2)
	v_mfma_f32_16x16x32_f16 v[244:247], v[232:235], v[72:75], v[244:247]
	s_waitcnt vmcnt(1)
	v_mfma_f32_16x16x32_f16 v[244:247], v[236:239], v[68:71], v[244:247]
	s_waitcnt vmcnt(0)
	v_mfma_f32_16x16x32_f16 v[4:7], v[240:243], v[4:7], v[244:247]
	s_branch .LBB0_526

; __device__ __forceinline__ float ex2(float x) { return __builtin_amdgcn_exp2f(x); }
;     __device__ __forceinline__ void mid(f32x4 (&acc)[2][2][4][2], const pg8::Unit& u, int wr, int wc, int fr, int fq) const {
;         const int row0 = u.pm * 256 + wr * 64 + fr, col0 = u.pn * 256 + wc * 32 + 8 * fq;
;         unsigned base = (unsigned)(row0 * NIN + col0);
;         asm volatile("" : "+v"(base));
;         const half_t* bp0 = P + base;
; #pragma unroll
;         for (int ai = 0; ai < 2; ++ai)
; #pragma unroll
;             for (int m = 0; m < 4; ++m) { const half_t* rowp = bp0 + (size_t)(ai * 128 + m * 16) * NIN;
;                 __builtin_amdgcn_sched_barrier(0);
; #pragma unroll
;                 for (int bj = 0; bj < 2; ++bj) { const h8 ga = *(const h8*)(rowp + C_MR + bj * 128), gb = *(const h8*)(rowp + C_MS + bj * 128);
; #pragma unroll
;                     for (int n = 0; n < 2; ++n)
; #pragma unroll
;                         for (int i = 0; i < 4; ++i) { const float a = (float)ga[4 * n + i], b = (float)gb[4 * n + i];
;                             acc[ai][bj][m][n][i] *= (1.f + ex2(b * -1.44269504f)) * __builtin_amdgcn_rcpf(1.f + ex2(a * -1.44269504f)); } } }
.LBB0_595:
	s_cmpk_lg_i32 s12, 0x1000
	s_cbranch_scc1 .LBB0_594
	v_mov_b32_e32 v2, v170
	s_nop 0
	v_lshl_add_u64 v[0:1], v[2:3], 1, s[36:37]
	v_add_co_u32_e32 v244, vcc, 0x6000, v0
	s_nop 1
	v_addc_co_u32_e32 v245, vcc, 0, v1, vcc
	global_load_dwordx4 v[196:199], v[244:245], off offset:-2048
	global_load_dwordx4 v[200:203], v[244:245], off offset:2048
	global_load_dwordx4 v[204:207], v[244:245], off offset:-1792
	global_load_dwordx4 v[208:211], v[244:245], off offset:2304
	v_add_co_u32_e32 v244, vcc, 0x7e000, v0
	s_nop 1
	v_addc_co_u32_e32 v245, vcc, 0, v1, vcc
	global_load_dwordx4 v[212:215], v[244:245], off offset:-2048
	global_load_dwordx4 v[216:219], v[244:245], off offset:2048
	global_load_dwordx4 v[220:223], v[244:245], off offset:-1792
	global_load_dwordx4 v[224:227], v[244:245], off offset:2304
	v_add_co_u32_e32 v244, vcc, 0xf6000, v0
	s_nop 1
	v_addc_co_u32_e32 v245, vcc, 0, v1, vcc
	global_load_dwordx4 v[228:231], v[244:245], off offset:-2048
	global_load_dwordx4 v[232:235], v[244:245], off offset:2048
	global_load_dwordx4 v[236:239], v[244:245], off offset:-1792
	global_load_dwordx4 v[240:243], v[244:245], off offset:2304
	v_add_co_u32_e32 v132, vcc, 0x5000, v0
	s_nop 1
	v_addc_co_u32_e32 v133, vcc, 0, v1, vcc
	s_waitcnt vmcnt(8)
	v_mov_b32_e32 v176, v196
	v_mov_b32_e32 v177, v197
	v_mov_b32_e32 v178, v198
	v_mov_b32_e32 v179, v199
	v_add_co_u32_e32 v136, vcc, 0x6000, v0
	s_nop 1
	v_addc_co_u32_e32 v137, vcc, 0, v1, vcc
	v_mov_b32_e32 v192, v200
	v_mov_b32_e32 v193, v201
	v_mov_b32_e32 v194, v202
	v_mov_b32_e32 v195, v203
	s_nop 0
	v_cvt_f32_f16_e32 v2, v176
	v_mul_f32_e32 v2, 0xbfb8aa3b, v2
	v_exp_f32_e32 v2, v2
	v_cvt_f32_f16_e32 v134, v192
	v_cvt_f32_f16_sdwa v135, v192 dst_sel:DWORD dst_unused:UNUSED_PAD src0_sel:WORD_1
	v_cvt_f32_f16_e32 v167, v193
	v_add_f32_e32 v2, 1.0, v2
	v_rcp_f32_e32 v138, v2
	v_cvt_f32_f16_sdwa v2, v176 dst_sel:DWORD dst_unused:UNUSED_PAD src0_sel:WORD_1
	v_mul_f32_e32 v167, 0xbfb8aa3b, v167
	v_exp_f32_e32 v176, v167
	v_cvt_f32_f16_sdwa v167, v193 dst_sel:DWORD dst_unused:UNUSED_PAD src0_sel:WORD_1
	v_mul_f32_e32 v2, 0xbfb8aa3b, v2
	v_exp_f32_e32 v2, v2
	v_mul_f32_e32 v134, 0xbfb8aa3b, v134
	v_mul_f32_e32 v135, 0xbfb8aa3b, v135
	v_mul_f32_e32 v167, 0xbfb8aa3b, v167
	v_add_f32_e32 v2, 1.0, v2
	v_rcp_f32_e32 v139, v2
	v_cvt_f32_f16_e32 v2, v177
	v_exp_f32_e32 v134, v134
	v_exp_f32_e32 v135, v135
	v_mul_f32_e32 v2, 0xbfb8aa3b, v2
	v_exp_f32_e32 v2, v2
	v_pk_add_f32 v[134:135], v[134:135], 1.0 op_sel_hi:[1,0]
	v_add_f32_e32 v2, 1.0, v2
	v_rcp_f32_e32 v192, v2
	v_cvt_f32_f16_sdwa v2, v177 dst_sel:DWORD dst_unused:UNUSED_PAD src0_sel:WORD_1
	v_exp_f32_e32 v177, v167
	v_pk_mul_f32 v[134:135], v[134:135], v[138:139]
	v_cvt_f32_f16_e32 v167, v195
	v_mul_f32_e32 v2, 0xbfb8aa3b, v2
	v_exp_f32_e32 v2, v2
	v_pk_add_f32 v[176:177], v[176:177], 1.0 op_sel_hi:[1,0]
	v_pk_mul_f32 v[128:129], v[128:129], v[134:135]
	v_cvt_f32_f16_e32 v134, v194
	v_add_f32_e32 v2, 1.0, v2
	v_rcp_f32_e32 v193, v2
	v_cvt_f32_f16_e32 v2, v178
	v_cvt_f32_f16_sdwa v135, v194 dst_sel:DWORD dst_unused:UNUSED_PAD src0_sel:WORD_1
	v_mul_f32_e32 v134, 0xbfb8aa3b, v134
	v_pk_mul_f32 v[138:139], v[176:177], v[192:193]
	v_mul_f32_e32 v2, 0xbfb8aa3b, v2
	v_exp_f32_e32 v2, v2
	v_pk_mul_f32 v[130:131], v[130:131], v[138:139]
	v_mul_f32_e32 v135, 0xbfb8aa3b, v135
	v_exp_f32_e32 v134, v134
	v_add_f32_e32 v2, 1.0, v2
	v_rcp_f32_e32 v138, v2
	v_cvt_f32_f16_sdwa v2, v178 dst_sel:DWORD dst_unused:UNUSED_PAD src0_sel:WORD_1
	v_exp_f32_e32 v135, v135
	v_mul_f32_e32 v167, 0xbfb8aa3b, v167
	v_exp_f32_e32 v176, v167
	v_mul_f32_e32 v2, 0xbfb8aa3b, v2
	v_exp_f32_e32 v2, v2
	v_pk_add_f32 v[134:135], v[134:135], 1.0 op_sel_hi:[1,0]
	v_cvt_f32_f16_sdwa v167, v195 dst_sel:DWORD dst_unused:UNUSED_PAD src0_sel:WORD_1
	v_add_f32_e32 v2, 1.0, v2
	v_rcp_f32_e32 v139, v2
	v_cvt_f32_f16_e32 v2, v179
	v_mul_f32_e32 v167, 0xbfb8aa3b, v167
	v_exp_f32_e32 v177, v167
	v_pk_mul_f32 v[134:135], v[134:135], v[138:139]
	v_mul_f32_e32 v2, 0xbfb8aa3b, v2
	v_pk_mul_f32 v[124:125], v[124:125], v[134:135]
	v_mov_b32_e32 v132, v204
	v_mov_b32_e32 v133, v205
	v_mov_b32_e32 v134, v206
	v_mov_b32_e32 v135, v207
	v_exp_f32_e32 v2, v2
	v_pk_add_f32 v[176:177], v[176:177], 1.0 op_sel_hi:[1,0]
	v_add_f32_e32 v2, 1.0, v2
	v_rcp_f32_e32 v178, v2
	v_cvt_f32_f16_sdwa v2, v179 dst_sel:DWORD dst_unused:UNUSED_PAD src0_sel:WORD_1
	v_mul_f32_e32 v2, 0xbfb8aa3b, v2
	v_exp_f32_e32 v2, v2
	s_nop 0
	v_add_f32_e32 v2, 1.0, v2
	v_rcp_f32_e32 v179, v2
	s_nop 0
	v_pk_mul_f32 v[138:139], v[176:177], v[178:179]
	s_nop 0
	v_pk_mul_f32 v[126:127], v[126:127], v[138:139]
	v_mov_b32_e32 v136, v208
	v_mov_b32_e32 v137, v209
	v_mov_b32_e32 v138, v210
	v_mov_b32_e32 v139, v211
	v_add_co_u32_e32 v244, vcc, 0x16e000, v0
	s_nop 1
	v_addc_co_u32_e32 v245, vcc, 0, v1, vcc
	global_load_dwordx4 v[196:199], v[244:245], off offset:-2048
	global_load_dwordx4 v[200:203], v[244:245], off offset:2048
	global_load_dwordx4 v[204:207], v[244:245], off offset:-1792
	global_load_dwordx4 v[208:211], v[244:245], off offset:2304
	s_nop 0
	v_cvt_f32_f16_e32 v2, v132
	v_mul_f32_e32 v2, 0xbfb8aa3b, v2
	v_exp_f32_e32 v2, v2
	v_cvt_f32_f16_e32 v167, v136
	v_add_f32_e32 v2, 1.0, v2
	v_rcp_f32_e32 v178, v2
	v_cvt_f32_f16_sdwa v2, v132 dst_sel:DWORD dst_unused:UNUSED_PAD src0_sel:WORD_1
	v_cvt_f32_f16_sdwa v132, v136 dst_sel:DWORD dst_unused:UNUSED_PAD src0_sel:WORD_1
	v_mul_f32_e32 v167, 0xbfb8aa3b, v167
	v_exp_f32_e32 v176, v167
	v_mul_f32_e32 v2, 0xbfb8aa3b, v2
	v_exp_f32_e32 v2, v2
	v_mul_f32_e32 v132, 0xbfb8aa3b, v132
	v_exp_f32_e32 v177, v132
	v_cvt_f32_f16_e32 v132, v137
	v_add_f32_e32 v2, 1.0, v2
	v_rcp_f32_e32 v179, v2
	v_cvt_f32_f16_e32 v2, v133
; __device__ __forceinline__ float ex2(float x) { return __builtin_amdgcn_exp2f(x); }
;     __device__ __forceinline__ void mid(f32x4 (&acc)[2][2][4][2], const pg8::Unit& u, int wr, int wc, int fr, int fq) const {
;         const int row0 = u.pm * 256 + wr * 64 + fr, col0 = u.pn * 256 + wc * 32 + 8 * fq;
;         unsigned base = (unsigned)(row0 * NIN + col0);
;         asm volatile("" : "+v"(base));
;         const half_t* bp0 = P + base;
; #pragma unroll
;         for (int ai = 0; ai < 2; ++ai)
; #pragma unroll
;             for (int m = 0; m < 4; ++m) { const half_t* rowp = bp0 + (size_t)(ai * 128 + m * 16) * NIN;
;                 __builtin_amdgcn_sched_barrier(0);
; #pragma unroll
;                 for (int bj = 0; bj < 2; ++bj) { const h8 ga = *(const h8*)(rowp + C_MR + bj * 128), gb = *(const h8*)(rowp + C_MS + bj * 128);
; #pragma unroll
;                     for (int n = 0; n < 2; ++n)
; #pragma unroll
;                         for (int i = 0; i < 4; ++i) { const float a = (float)ga[4 * n + i], b = (float)gb[4 * n + i];
;                             acc[ai][bj][m][n][i] *= (1.f + ex2(b * -1.44269504f)) * __builtin_amdgcn_rcpf(1.f + ex2(a * -1.44269504f)); } } }
	v_mul_f32_e32 v132, 0xbfb8aa3b, v132
	v_exp_f32_e32 v132, v132
	v_pk_add_f32 v[176:177], v[176:177], 1.0 op_sel_hi:[1,0]
	v_mul_f32_e32 v2, 0xbfb8aa3b, v2
	v_exp_f32_e32 v2, v2
	v_pk_mul_f32 v[176:177], v[176:177], v[178:179]
	v_add_f32_e32 v2, 1.0, v2
	v_rcp_f32_e32 v136, v2
	v_cvt_f32_f16_sdwa v2, v133 dst_sel:DWORD dst_unused:UNUSED_PAD src0_sel:WORD_1
	v_cvt_f32_f16_sdwa v133, v137 dst_sel:DWORD dst_unused:UNUSED_PAD src0_sel:WORD_1
	v_pk_mul_f32 v[120:121], v[120:121], v[176:177]
	v_mul_f32_e32 v2, 0xbfb8aa3b, v2
	v_exp_f32_e32 v2, v2
	v_mul_f32_e32 v133, 0xbfb8aa3b, v133
	v_exp_f32_e32 v133, v133
	v_add_f32_e32 v2, 1.0, v2
	v_rcp_f32_e32 v137, v2
	v_cvt_f32_f16_e32 v2, v134
	v_pk_add_f32 v[132:133], v[132:133], 1.0 op_sel_hi:[1,0]
	v_mul_f32_e32 v2, 0xbfb8aa3b, v2
	v_exp_f32_e32 v2, v2
	v_pk_mul_f32 v[132:133], v[132:133], v[136:137]
	v_add_f32_e32 v2, 1.0, v2
	v_rcp_f32_e32 v136, v2
	v_cvt_f32_f16_sdwa v2, v134 dst_sel:DWORD dst_unused:UNUSED_PAD src0_sel:WORD_1
	v_pk_mul_f32 v[122:123], v[122:123], v[132:133]
	v_cvt_f32_f16_e32 v132, v138
	v_cvt_f32_f16_sdwa v133, v138 dst_sel:DWORD dst_unused:UNUSED_PAD src0_sel:WORD_1
	v_mul_f32_e32 v2, 0xbfb8aa3b, v2
	v_exp_f32_e32 v2, v2
	v_cvt_f32_f16_e32 v134, v139
	v_mul_f32_e32 v132, 0xbfb8aa3b, v132
	v_mul_f32_e32 v133, 0xbfb8aa3b, v133
	v_add_f32_e32 v2, 1.0, v2
	v_rcp_f32_e32 v137, v2
	v_cvt_f32_f16_e32 v2, v135
	v_mul_f32_e32 v134, 0xbfb8aa3b, v134
	v_exp_f32_e32 v132, v132
	v_exp_f32_e32 v133, v133
	v_mul_f32_e32 v2, 0xbfb8aa3b, v2
	v_exp_f32_e32 v2, v2
	v_exp_f32_e32 v134, v134
	v_pk_add_f32 v[132:133], v[132:133], 1.0 op_sel_hi:[1,0]
	v_add_f32_e32 v2, 1.0, v2
	v_rcp_f32_e32 v138, v2
	v_cvt_f32_f16_sdwa v2, v135 dst_sel:DWORD dst_unused:UNUSED_PAD src0_sel:WORD_1
	v_cvt_f32_f16_sdwa v135, v139 dst_sel:DWORD dst_unused:UNUSED_PAD src0_sel:WORD_1
	v_pk_mul_f32 v[132:133], v[132:133], v[136:137]
	v_mul_f32_e32 v2, 0xbfb8aa3b, v2
	v_exp_f32_e32 v2, v2
	v_mul_f32_e32 v135, 0xbfb8aa3b, v135
	v_exp_f32_e32 v135, v135
	v_pk_mul_f32 v[116:117], v[116:117], v[132:133]
	v_add_f32_e32 v2, 1.0, v2
	v_rcp_f32_e32 v139, v2
	v_pk_add_f32 v[134:135], v[134:135], 1.0 op_sel_hi:[1,0]
	s_nop 0
	v_pk_mul_f32 v[134:135], v[134:135], v[138:139]
	s_nop 0
	v_pk_mul_f32 v[118:119], v[118:119], v[134:135]
	s_mov_b32 s14, 0x7d000
	v_add_co_u32_e32 v132, vcc, s14, v0
	s_mov_b32 s14, 0x7e000
	s_nop 0
	v_addc_co_u32_e32 v133, vcc, 0, v1, vcc
	s_waitcnt vmcnt(8)
	v_mov_b32_e32 v176, v212
	v_mov_b32_e32 v177, v213
	v_mov_b32_e32 v178, v214
	v_mov_b32_e32 v179, v215
	v_add_co_u32_e32 v136, vcc, s14, v0
	s_nop 1
	v_addc_co_u32_e32 v137, vcc, 0, v1, vcc
	v_mov_b32_e32 v192, v216
	v_mov_b32_e32 v193, v217
	v_mov_b32_e32 v194, v218
	v_mov_b32_e32 v195, v219
	s_nop 0
	v_cvt_f32_f16_e32 v2, v176
	v_mul_f32_e32 v2, 0xbfb8aa3b, v2
	v_exp_f32_e32 v2, v2
	v_cvt_f32_f16_e32 v134, v192
	v_cvt_f32_f16_sdwa v135, v192 dst_sel:DWORD dst_unused:UNUSED_PAD src0_sel:WORD_1
	v_cvt_f32_f16_e32 v167, v193
	v_add_f32_e32 v2, 1.0, v2
	v_rcp_f32_e32 v138, v2
	v_cvt_f32_f16_sdwa v2, v176 dst_sel:DWORD dst_unused:UNUSED_PAD src0_sel:WORD_1
	v_mul_f32_e32 v167, 0xbfb8aa3b, v167
	v_exp_f32_e32 v176, v167
	v_cvt_f32_f16_sdwa v167, v193 dst_sel:DWORD dst_unused:UNUSED_PAD src0_sel:WORD_1
	v_mul_f32_e32 v2, 0xbfb8aa3b, v2
	v_exp_f32_e32 v2, v2
	v_mul_f32_e32 v134, 0xbfb8aa3b, v134
	v_mul_f32_e32 v135, 0xbfb8aa3b, v135
	v_mul_f32_e32 v167, 0xbfb8aa3b, v167
	v_add_f32_e32 v2, 1.0, v2
	v_rcp_f32_e32 v139, v2
	v_cvt_f32_f16_e32 v2, v177
	v_exp_f32_e32 v134, v134
	v_exp_f32_e32 v135, v135
	v_mul_f32_e32 v2, 0xbfb8aa3b, v2
	v_exp_f32_e32 v2, v2
	v_pk_add_f32 v[134:135], v[134:135], 1.0 op_sel_hi:[1,0]
	v_add_f32_e32 v2, 1.0, v2
	v_rcp_f32_e32 v192, v2
	v_cvt_f32_f16_sdwa v2, v177 dst_sel:DWORD dst_unused:UNUSED_PAD src0_sel:WORD_1
	v_exp_f32_e32 v177, v167
	v_pk_mul_f32 v[134:135], v[134:135], v[138:139]
	v_cvt_f32_f16_e32 v167, v195
	v_mul_f32_e32 v2, 0xbfb8aa3b, v2
	v_exp_f32_e32 v2, v2
	v_pk_add_f32 v[176:177], v[176:177], 1.0 op_sel_hi:[1,0]
	v_pk_mul_f32 v[112:113], v[112:113], v[134:135]
	v_cvt_f32_f16_e32 v134, v194
	v_add_f32_e32 v2, 1.0, v2
	v_rcp_f32_e32 v193, v2
	v_cvt_f32_f16_e32 v2, v178
	v_cvt_f32_f16_sdwa v135, v194 dst_sel:DWORD dst_unused:UNUSED_PAD src0_sel:WORD_1
	v_mul_f32_e32 v134, 0xbfb8aa3b, v134
	v_pk_mul_f32 v[138:139], v[176:177], v[192:193]
	v_mul_f32_e32 v2, 0xbfb8aa3b, v2
	v_exp_f32_e32 v2, v2
	v_pk_mul_f32 v[114:115], v[114:115], v[138:139]
	v_mul_f32_e32 v135, 0xbfb8aa3b, v135
	v_exp_f32_e32 v134, v134
	v_add_f32_e32 v2, 1.0, v2
	v_rcp_f32_e32 v138, v2
	v_cvt_f32_f16_sdwa v2, v178 dst_sel:DWORD dst_unused:UNUSED_PAD src0_sel:WORD_1
	v_exp_f32_e32 v135, v135
	v_mul_f32_e32 v167, 0xbfb8aa3b, v167
	v_exp_f32_e32 v176, v167
	v_mul_f32_e32 v2, 0xbfb8aa3b, v2
	v_exp_f32_e32 v2, v2
	v_pk_add_f32 v[134:135], v[134:135], 1.0 op_sel_hi:[1,0]
	v_cvt_f32_f16_sdwa v167, v195 dst_sel:DWORD dst_unused:UNUSED_PAD src0_sel:WORD_1
	v_add_f32_e32 v2, 1.0, v2
	v_rcp_f32_e32 v139, v2
	v_cvt_f32_f16_e32 v2, v179
	v_mul_f32_e32 v167, 0xbfb8aa3b, v167
	v_exp_f32_e32 v177, v167
	v_pk_mul_f32 v[134:135], v[134:135], v[138:139]
	v_mul_f32_e32 v2, 0xbfb8aa3b, v2
	v_pk_mul_f32 v[108:109], v[108:109], v[134:135]
	v_mov_b32_e32 v132, v220
	v_mov_b32_e32 v133, v221
	v_mov_b32_e32 v134, v222
	v_mov_b32_e32 v135, v223
	v_exp_f32_e32 v2, v2
	v_pk_add_f32 v[176:177], v[176:177], 1.0 op_sel_hi:[1,0]
	v_add_f32_e32 v2, 1.0, v2
	v_rcp_f32_e32 v178, v2
	v_cvt_f32_f16_sdwa v2, v179 dst_sel:DWORD dst_unused:UNUSED_PAD src0_sel:WORD_1
	v_mul_f32_e32 v2, 0xbfb8aa3b, v2
	v_exp_f32_e32 v2, v2
	s_nop 0
	v_add_f32_e32 v2, 1.0, v2
	v_rcp_f32_e32 v179, v2
	s_nop 0
; __device__ __forceinline__ float ex2(float x) { return __builtin_amdgcn_exp2f(x); }
;     __device__ __forceinline__ void mid(f32x4 (&acc)[2][2][4][2], const pg8::Unit& u, int wr, int wc, int fr, int fq) const {
;         const int row0 = u.pm * 256 + wr * 64 + fr, col0 = u.pn * 256 + wc * 32 + 8 * fq;
;         unsigned base = (unsigned)(row0 * NIN + col0);
;         asm volatile("" : "+v"(base));
;         const half_t* bp0 = P + base;
; #pragma unroll
;         for (int ai = 0; ai < 2; ++ai)
; #pragma unroll
;             for (int m = 0; m < 4; ++m) { const half_t* rowp = bp0 + (size_t)(ai * 128 + m * 16) * NIN;
;                 __builtin_amdgcn_sched_barrier(0);
; #pragma unroll
;                 for (int bj = 0; bj < 2; ++bj) { const h8 ga = *(const h8*)(rowp + C_MR + bj * 128), gb = *(const h8*)(rowp + C_MS + bj * 128);
; #pragma unroll
;                     for (int n = 0; n < 2; ++n)
; #pragma unroll
;                         for (int i = 0; i < 4; ++i) { const float a = (float)ga[4 * n + i], b = (float)gb[4 * n + i];
;                             acc[ai][bj][m][n][i] *= (1.f + ex2(b * -1.44269504f)) * __builtin_amdgcn_rcpf(1.f + ex2(a * -1.44269504f)); } } }
	v_pk_mul_f32 v[138:139], v[176:177], v[178:179]
	s_nop 0
	v_pk_mul_f32 v[110:111], v[110:111], v[138:139]
	v_mov_b32_e32 v136, v224
	v_mov_b32_e32 v137, v225
	v_mov_b32_e32 v138, v226
	v_mov_b32_e32 v139, v227
	v_add_co_u32_e32 v244, vcc, 0x3c6000, v0
	s_nop 1
	v_addc_co_u32_e32 v245, vcc, 0, v1, vcc
	global_load_dwordx4 v[212:215], v[244:245], off offset:-2048
	global_load_dwordx4 v[216:219], v[244:245], off offset:2048
	global_load_dwordx4 v[220:223], v[244:245], off offset:-1792
	global_load_dwordx4 v[224:227], v[244:245], off offset:2304
	s_nop 0
	v_cvt_f32_f16_e32 v2, v132
	v_mul_f32_e32 v2, 0xbfb8aa3b, v2
	v_exp_f32_e32 v2, v2
	v_cvt_f32_f16_e32 v167, v136
	v_add_f32_e32 v2, 1.0, v2
	v_rcp_f32_e32 v178, v2
	v_cvt_f32_f16_sdwa v2, v132 dst_sel:DWORD dst_unused:UNUSED_PAD src0_sel:WORD_1
	v_cvt_f32_f16_sdwa v132, v136 dst_sel:DWORD dst_unused:UNUSED_PAD src0_sel:WORD_1
	v_mul_f32_e32 v167, 0xbfb8aa3b, v167
	v_exp_f32_e32 v176, v167
	v_mul_f32_e32 v2, 0xbfb8aa3b, v2
	v_exp_f32_e32 v2, v2
	v_mul_f32_e32 v132, 0xbfb8aa3b, v132
	v_exp_f32_e32 v177, v132
	v_cvt_f32_f16_e32 v132, v137
	v_add_f32_e32 v2, 1.0, v2
	v_rcp_f32_e32 v179, v2
	v_cvt_f32_f16_e32 v2, v133
	v_mul_f32_e32 v132, 0xbfb8aa3b, v132
	v_exp_f32_e32 v132, v132
	v_pk_add_f32 v[176:177], v[176:177], 1.0 op_sel_hi:[1,0]
	v_mul_f32_e32 v2, 0xbfb8aa3b, v2
	v_exp_f32_e32 v2, v2
	v_pk_mul_f32 v[176:177], v[176:177], v[178:179]
	v_add_f32_e32 v2, 1.0, v2
	v_rcp_f32_e32 v136, v2
	v_cvt_f32_f16_sdwa v2, v133 dst_sel:DWORD dst_unused:UNUSED_PAD src0_sel:WORD_1
	v_cvt_f32_f16_sdwa v133, v137 dst_sel:DWORD dst_unused:UNUSED_PAD src0_sel:WORD_1
	v_pk_mul_f32 v[104:105], v[104:105], v[176:177]
	v_mul_f32_e32 v2, 0xbfb8aa3b, v2
	v_exp_f32_e32 v2, v2
	v_mul_f32_e32 v133, 0xbfb8aa3b, v133
	v_exp_f32_e32 v133, v133
	v_add_f32_e32 v2, 1.0, v2
	v_rcp_f32_e32 v137, v2
	v_cvt_f32_f16_e32 v2, v134
	v_pk_add_f32 v[132:133], v[132:133], 1.0 op_sel_hi:[1,0]
	v_mul_f32_e32 v2, 0xbfb8aa3b, v2
	v_exp_f32_e32 v2, v2
	v_pk_mul_f32 v[132:133], v[132:133], v[136:137]
	v_add_f32_e32 v2, 1.0, v2
	v_rcp_f32_e32 v136, v2
	v_cvt_f32_f16_sdwa v2, v134 dst_sel:DWORD dst_unused:UNUSED_PAD src0_sel:WORD_1
	v_pk_mul_f32 v[106:107], v[106:107], v[132:133]
	v_cvt_f32_f16_e32 v132, v138
	v_cvt_f32_f16_sdwa v133, v138 dst_sel:DWORD dst_unused:UNUSED_PAD src0_sel:WORD_1
	v_mul_f32_e32 v2, 0xbfb8aa3b, v2
	v_exp_f32_e32 v2, v2
	v_cvt_f32_f16_e32 v134, v139
	v_mul_f32_e32 v132, 0xbfb8aa3b, v132
	v_mul_f32_e32 v133, 0xbfb8aa3b, v133
	v_add_f32_e32 v2, 1.0, v2
	v_rcp_f32_e32 v137, v2
	v_cvt_f32_f16_e32 v2, v135
	v_mul_f32_e32 v134, 0xbfb8aa3b, v134
	v_exp_f32_e32 v132, v132
	v_exp_f32_e32 v133, v133
	v_mul_f32_e32 v2, 0xbfb8aa3b, v2
	v_exp_f32_e32 v2, v2
	v_exp_f32_e32 v134, v134
	v_pk_add_f32 v[132:133], v[132:133], 1.0 op_sel_hi:[1,0]
	v_add_f32_e32 v2, 1.0, v2
	v_rcp_f32_e32 v138, v2
	v_cvt_f32_f16_sdwa v2, v135 dst_sel:DWORD dst_unused:UNUSED_PAD src0_sel:WORD_1
	v_cvt_f32_f16_sdwa v135, v139 dst_sel:DWORD dst_unused:UNUSED_PAD src0_sel:WORD_1
	v_pk_mul_f32 v[132:133], v[132:133], v[136:137]
	v_mul_f32_e32 v2, 0xbfb8aa3b, v2
	v_exp_f32_e32 v2, v2
	v_mul_f32_e32 v135, 0xbfb8aa3b, v135
	v_exp_f32_e32 v135, v135
	v_pk_mul_f32 v[100:101], v[100:101], v[132:133]
	v_add_f32_e32 v2, 1.0, v2
	v_rcp_f32_e32 v139, v2
	v_pk_add_f32 v[134:135], v[134:135], 1.0 op_sel_hi:[1,0]
	s_nop 0
	v_pk_mul_f32 v[134:135], v[134:135], v[138:139]
	s_nop 0
	v_pk_mul_f32 v[102:103], v[102:103], v[134:135]
	s_mov_b32 s14, 0xf5000
	v_add_co_u32_e32 v132, vcc, s14, v0
	s_mov_b32 s14, 0xf6000
	s_nop 0
	v_addc_co_u32_e32 v133, vcc, 0, v1, vcc
	s_waitcnt vmcnt(8)
	v_mov_b32_e32 v176, v228
	v_mov_b32_e32 v177, v229
	v_mov_b32_e32 v178, v230
	v_mov_b32_e32 v179, v231
	v_add_co_u32_e32 v136, vcc, s14, v0
	s_nop 1
	v_addc_co_u32_e32 v137, vcc, 0, v1, vcc
	v_mov_b32_e32 v192, v232
	v_mov_b32_e32 v193, v233
	v_mov_b32_e32 v194, v234
	v_mov_b32_e32 v195, v235
	s_nop 0
	v_cvt_f32_f16_e32 v2, v176
	v_mul_f32_e32 v2, 0xbfb8aa3b, v2
	v_exp_f32_e32 v2, v2
	v_cvt_f32_f16_e32 v134, v192
	v_cvt_f32_f16_sdwa v135, v192 dst_sel:DWORD dst_unused:UNUSED_PAD src0_sel:WORD_1
	v_cvt_f32_f16_e32 v167, v193
	v_add_f32_e32 v2, 1.0, v2
	v_rcp_f32_e32 v138, v2
	v_cvt_f32_f16_sdwa v2, v176 dst_sel:DWORD dst_unused:UNUSED_PAD src0_sel:WORD_1
	v_mul_f32_e32 v167, 0xbfb8aa3b, v167
	v_exp_f32_e32 v176, v167
	v_cvt_f32_f16_sdwa v167, v193 dst_sel:DWORD dst_unused:UNUSED_PAD src0_sel:WORD_1
	v_mul_f32_e32 v2, 0xbfb8aa3b, v2
	v_exp_f32_e32 v2, v2
	v_mul_f32_e32 v134, 0xbfb8aa3b, v134
	v_mul_f32_e32 v135, 0xbfb8aa3b, v135
	v_mul_f32_e32 v167, 0xbfb8aa3b, v167
	v_add_f32_e32 v2, 1.0, v2
	v_rcp_f32_e32 v139, v2
	v_cvt_f32_f16_e32 v2, v177
	v_exp_f32_e32 v134, v134
	v_exp_f32_e32 v135, v135
	v_mul_f32_e32 v2, 0xbfb8aa3b, v2
	v_exp_f32_e32 v2, v2
	v_pk_add_f32 v[134:135], v[134:135], 1.0 op_sel_hi:[1,0]
	v_add_f32_e32 v2, 1.0, v2
	v_rcp_f32_e32 v192, v2
	v_cvt_f32_f16_sdwa v2, v177 dst_sel:DWORD dst_unused:UNUSED_PAD src0_sel:WORD_1
	v_exp_f32_e32 v177, v167
	v_pk_mul_f32 v[134:135], v[134:135], v[138:139]
	v_cvt_f32_f16_e32 v167, v195
	v_mul_f32_e32 v2, 0xbfb8aa3b, v2
	v_exp_f32_e32 v2, v2
	v_pk_add_f32 v[176:177], v[176:177], 1.0 op_sel_hi:[1,0]
	v_pk_mul_f32 v[96:97], v[96:97], v[134:135]
	v_cvt_f32_f16_e32 v134, v194
	v_add_f32_e32 v2, 1.0, v2
	v_rcp_f32_e32 v193, v2
	v_cvt_f32_f16_e32 v2, v178
	v_cvt_f32_f16_sdwa v135, v194 dst_sel:DWORD dst_unused:UNUSED_PAD src0_sel:WORD_1
	v_mul_f32_e32 v134, 0xbfb8aa3b, v134
	v_pk_mul_f32 v[138:139], v[176:177], v[192:193]
	v_mul_f32_e32 v2, 0xbfb8aa3b, v2
	v_exp_f32_e32 v2, v2
	v_pk_mul_f32 v[98:99], v[98:99], v[138:139]
	v_mul_f32_e32 v135, 0xbfb8aa3b, v135
; __device__ __forceinline__ float ex2(float x) { return __builtin_amdgcn_exp2f(x); }
;     __device__ __forceinline__ void mid(f32x4 (&acc)[2][2][4][2], const pg8::Unit& u, int wr, int wc, int fr, int fq) const {
;         const int row0 = u.pm * 256 + wr * 64 + fr, col0 = u.pn * 256 + wc * 32 + 8 * fq;
;         unsigned base = (unsigned)(row0 * NIN + col0);
;         asm volatile("" : "+v"(base));
;         const half_t* bp0 = P + base;
; #pragma unroll
;         for (int ai = 0; ai < 2; ++ai)
; #pragma unroll
;             for (int m = 0; m < 4; ++m) { const half_t* rowp = bp0 + (size_t)(ai * 128 + m * 16) * NIN;
;                 __builtin_amdgcn_sched_barrier(0);
; #pragma unroll
;                 for (int bj = 0; bj < 2; ++bj) { const h8 ga = *(const h8*)(rowp + C_MR + bj * 128), gb = *(const h8*)(rowp + C_MS + bj * 128);
; #pragma unroll
;                     for (int n = 0; n < 2; ++n)
; #pragma unroll
;                         for (int i = 0; i < 4; ++i) { const float a = (float)ga[4 * n + i], b = (float)gb[4 * n + i];
;                             acc[ai][bj][m][n][i] *= (1.f + ex2(b * -1.44269504f)) * __builtin_amdgcn_rcpf(1.f + ex2(a * -1.44269504f)); } } }
	v_exp_f32_e32 v134, v134
	v_add_f32_e32 v2, 1.0, v2
	v_rcp_f32_e32 v138, v2
	v_cvt_f32_f16_sdwa v2, v178 dst_sel:DWORD dst_unused:UNUSED_PAD src0_sel:WORD_1
	v_exp_f32_e32 v135, v135
	v_mul_f32_e32 v167, 0xbfb8aa3b, v167
	v_exp_f32_e32 v176, v167
	v_mul_f32_e32 v2, 0xbfb8aa3b, v2
	v_exp_f32_e32 v2, v2
	v_pk_add_f32 v[134:135], v[134:135], 1.0 op_sel_hi:[1,0]
	v_cvt_f32_f16_sdwa v167, v195 dst_sel:DWORD dst_unused:UNUSED_PAD src0_sel:WORD_1
	v_add_f32_e32 v2, 1.0, v2
	v_rcp_f32_e32 v139, v2
	v_cvt_f32_f16_e32 v2, v179
	v_mul_f32_e32 v167, 0xbfb8aa3b, v167
	v_exp_f32_e32 v177, v167
	v_pk_mul_f32 v[134:135], v[134:135], v[138:139]
	v_mul_f32_e32 v2, 0xbfb8aa3b, v2
	v_pk_mul_f32 v[92:93], v[92:93], v[134:135]
	v_mov_b32_e32 v132, v236
	v_mov_b32_e32 v133, v237
	v_mov_b32_e32 v134, v238
	v_mov_b32_e32 v135, v239
	v_exp_f32_e32 v2, v2
	v_pk_add_f32 v[176:177], v[176:177], 1.0 op_sel_hi:[1,0]
	v_add_f32_e32 v2, 1.0, v2
	v_rcp_f32_e32 v178, v2
	v_cvt_f32_f16_sdwa v2, v179 dst_sel:DWORD dst_unused:UNUSED_PAD src0_sel:WORD_1
	v_mul_f32_e32 v2, 0xbfb8aa3b, v2
	v_exp_f32_e32 v2, v2
	s_nop 0
	v_add_f32_e32 v2, 1.0, v2
	v_rcp_f32_e32 v179, v2
	s_nop 0
	v_pk_mul_f32 v[138:139], v[176:177], v[178:179]
	s_nop 0
	v_pk_mul_f32 v[94:95], v[94:95], v[138:139]
	v_mov_b32_e32 v136, v240
	v_mov_b32_e32 v137, v241
	v_mov_b32_e32 v138, v242
	v_mov_b32_e32 v139, v243
	v_add_co_u32_e32 v244, vcc, 0x43e000, v0
	s_nop 1
	v_addc_co_u32_e32 v245, vcc, 0, v1, vcc
	global_load_dwordx4 v[228:231], v[244:245], off offset:-2048
	global_load_dwordx4 v[232:235], v[244:245], off offset:2048
	global_load_dwordx4 v[236:239], v[244:245], off offset:-1792
	global_load_dwordx4 v[240:243], v[244:245], off offset:2304
	s_nop 0
	v_cvt_f32_f16_e32 v2, v132
	v_mul_f32_e32 v2, 0xbfb8aa3b, v2
	v_exp_f32_e32 v2, v2
	v_cvt_f32_f16_e32 v167, v136
	v_add_f32_e32 v2, 1.0, v2
	v_rcp_f32_e32 v178, v2
	v_cvt_f32_f16_sdwa v2, v132 dst_sel:DWORD dst_unused:UNUSED_PAD src0_sel:WORD_1
	v_cvt_f32_f16_sdwa v132, v136 dst_sel:DWORD dst_unused:UNUSED_PAD src0_sel:WORD_1
	v_mul_f32_e32 v167, 0xbfb8aa3b, v167
	v_exp_f32_e32 v176, v167
	v_mul_f32_e32 v2, 0xbfb8aa3b, v2
	v_exp_f32_e32 v2, v2
	v_mul_f32_e32 v132, 0xbfb8aa3b, v132
	v_exp_f32_e32 v177, v132
	v_cvt_f32_f16_e32 v132, v137
	v_add_f32_e32 v2, 1.0, v2
	v_rcp_f32_e32 v179, v2
	v_cvt_f32_f16_e32 v2, v133
	v_mul_f32_e32 v132, 0xbfb8aa3b, v132
	v_exp_f32_e32 v132, v132
	v_pk_add_f32 v[176:177], v[176:177], 1.0 op_sel_hi:[1,0]
	v_mul_f32_e32 v2, 0xbfb8aa3b, v2
	v_exp_f32_e32 v2, v2
	v_pk_mul_f32 v[176:177], v[176:177], v[178:179]
	v_add_f32_e32 v2, 1.0, v2
	v_rcp_f32_e32 v136, v2
	v_cvt_f32_f16_sdwa v2, v133 dst_sel:DWORD dst_unused:UNUSED_PAD src0_sel:WORD_1
	v_cvt_f32_f16_sdwa v133, v137 dst_sel:DWORD dst_unused:UNUSED_PAD src0_sel:WORD_1
	v_pk_mul_f32 v[88:89], v[88:89], v[176:177]
	v_mul_f32_e32 v2, 0xbfb8aa3b, v2
	v_exp_f32_e32 v2, v2
	v_mul_f32_e32 v133, 0xbfb8aa3b, v133
	v_exp_f32_e32 v133, v133
	v_add_f32_e32 v2, 1.0, v2
	v_rcp_f32_e32 v137, v2
	v_cvt_f32_f16_e32 v2, v134
	v_pk_add_f32 v[132:133], v[132:133], 1.0 op_sel_hi:[1,0]
	v_mul_f32_e32 v2, 0xbfb8aa3b, v2
	v_exp_f32_e32 v2, v2
	v_pk_mul_f32 v[132:133], v[132:133], v[136:137]
	v_add_f32_e32 v2, 1.0, v2
	v_rcp_f32_e32 v136, v2
	v_cvt_f32_f16_sdwa v2, v134 dst_sel:DWORD dst_unused:UNUSED_PAD src0_sel:WORD_1
	v_pk_mul_f32 v[90:91], v[90:91], v[132:133]
	v_cvt_f32_f16_e32 v132, v138
	v_cvt_f32_f16_sdwa v133, v138 dst_sel:DWORD dst_unused:UNUSED_PAD src0_sel:WORD_1
	v_mul_f32_e32 v2, 0xbfb8aa3b, v2
	v_exp_f32_e32 v2, v2
	v_cvt_f32_f16_e32 v134, v139
	v_mul_f32_e32 v132, 0xbfb8aa3b, v132
	v_mul_f32_e32 v133, 0xbfb8aa3b, v133
	v_add_f32_e32 v2, 1.0, v2
	v_rcp_f32_e32 v137, v2
	v_cvt_f32_f16_e32 v2, v135
	v_mul_f32_e32 v134, 0xbfb8aa3b, v134
	v_exp_f32_e32 v132, v132
	v_exp_f32_e32 v133, v133
	v_mul_f32_e32 v2, 0xbfb8aa3b, v2
	v_exp_f32_e32 v2, v2
	v_exp_f32_e32 v134, v134
	v_pk_add_f32 v[132:133], v[132:133], 1.0 op_sel_hi:[1,0]
	v_add_f32_e32 v2, 1.0, v2
	v_rcp_f32_e32 v138, v2
	v_cvt_f32_f16_sdwa v2, v135 dst_sel:DWORD dst_unused:UNUSED_PAD src0_sel:WORD_1
	v_cvt_f32_f16_sdwa v135, v139 dst_sel:DWORD dst_unused:UNUSED_PAD src0_sel:WORD_1
	v_pk_mul_f32 v[132:133], v[132:133], v[136:137]
	v_mul_f32_e32 v2, 0xbfb8aa3b, v2
	v_exp_f32_e32 v2, v2
	v_mul_f32_e32 v135, 0xbfb8aa3b, v135
	v_exp_f32_e32 v135, v135
	v_pk_mul_f32 v[84:85], v[84:85], v[132:133]
	v_add_f32_e32 v2, 1.0, v2
	v_rcp_f32_e32 v139, v2
	v_pk_add_f32 v[134:135], v[134:135], 1.0 op_sel_hi:[1,0]
	s_nop 0
	v_pk_mul_f32 v[134:135], v[134:135], v[138:139]
	s_nop 0
	v_pk_mul_f32 v[86:87], v[86:87], v[134:135]
	s_mov_b32 s14, 0x16d000
	v_add_co_u32_e32 v132, vcc, s14, v0
	s_mov_b32 s14, 0x16e000
	s_nop 0
	v_addc_co_u32_e32 v133, vcc, 0, v1, vcc
	s_waitcnt vmcnt(8)
; __device__ __forceinline__ float ex2(float x) { return __builtin_amdgcn_exp2f(x); }
;     __device__ __forceinline__ void mid(f32x4 (&acc)[2][2][4][2], const pg8::Unit& u, int wr, int wc, int fr, int fq) const {
;         const int row0 = u.pm * 256 + wr * 64 + fr, col0 = u.pn * 256 + wc * 32 + 8 * fq;
;         unsigned base = (unsigned)(row0 * NIN + col0);
;         asm volatile("" : "+v"(base));
;         const half_t* bp0 = P + base;
; #pragma unroll
;         for (int ai = 0; ai < 2; ++ai)
; #pragma unroll
;             for (int m = 0; m < 4; ++m) { const half_t* rowp = bp0 + (size_t)(ai * 128 + m * 16) * NIN;
;                 __builtin_amdgcn_sched_barrier(0);
; #pragma unroll
;                 for (int bj = 0; bj < 2; ++bj) { const h8 ga = *(const h8*)(rowp + C_MR + bj * 128), gb = *(const h8*)(rowp + C_MS + bj * 128);
; #pragma unroll
;                     for (int n = 0; n < 2; ++n)
; #pragma unroll
;                         for (int i = 0; i < 4; ++i) { const float a = (float)ga[4 * n + i], b = (float)gb[4 * n + i];
;                             acc[ai][bj][m][n][i] *= (1.f + ex2(b * -1.44269504f)) * __builtin_amdgcn_rcpf(1.f + ex2(a * -1.44269504f)); } } }
	v_mov_b32_e32 v176, v196
	v_mov_b32_e32 v177, v197
	v_mov_b32_e32 v178, v198
	v_mov_b32_e32 v179, v199
	v_add_co_u32_e32 v136, vcc, s14, v0
	s_nop 1
	v_addc_co_u32_e32 v137, vcc, 0, v1, vcc
	v_mov_b32_e32 v192, v200
	v_mov_b32_e32 v193, v201
	v_mov_b32_e32 v194, v202
	v_mov_b32_e32 v195, v203
	s_nop 0
	v_cvt_f32_f16_e32 v2, v176
	v_mul_f32_e32 v2, 0xbfb8aa3b, v2
	v_exp_f32_e32 v2, v2
	v_cvt_f32_f16_e32 v134, v192
	v_cvt_f32_f16_sdwa v135, v192 dst_sel:DWORD dst_unused:UNUSED_PAD src0_sel:WORD_1
	v_cvt_f32_f16_e32 v167, v193
	v_add_f32_e32 v2, 1.0, v2
	v_rcp_f32_e32 v138, v2
	v_cvt_f32_f16_sdwa v2, v176 dst_sel:DWORD dst_unused:UNUSED_PAD src0_sel:WORD_1
	v_mul_f32_e32 v167, 0xbfb8aa3b, v167
	v_exp_f32_e32 v176, v167
	v_cvt_f32_f16_sdwa v167, v193 dst_sel:DWORD dst_unused:UNUSED_PAD src0_sel:WORD_1
	v_mul_f32_e32 v2, 0xbfb8aa3b, v2
	v_exp_f32_e32 v2, v2
	v_mul_f32_e32 v134, 0xbfb8aa3b, v134
	v_mul_f32_e32 v135, 0xbfb8aa3b, v135
	v_mul_f32_e32 v167, 0xbfb8aa3b, v167
	v_add_f32_e32 v2, 1.0, v2
	v_rcp_f32_e32 v139, v2
	v_cvt_f32_f16_e32 v2, v177
	v_exp_f32_e32 v134, v134
	v_exp_f32_e32 v135, v135
	v_mul_f32_e32 v2, 0xbfb8aa3b, v2
	v_exp_f32_e32 v2, v2
	v_pk_add_f32 v[134:135], v[134:135], 1.0 op_sel_hi:[1,0]
	v_add_f32_e32 v2, 1.0, v2
	v_rcp_f32_e32 v192, v2
	v_cvt_f32_f16_sdwa v2, v177 dst_sel:DWORD dst_unused:UNUSED_PAD src0_sel:WORD_1
	v_exp_f32_e32 v177, v167
	v_pk_mul_f32 v[134:135], v[134:135], v[138:139]
	v_cvt_f32_f16_e32 v167, v195
	v_mul_f32_e32 v2, 0xbfb8aa3b, v2
	v_exp_f32_e32 v2, v2
	v_pk_add_f32 v[176:177], v[176:177], 1.0 op_sel_hi:[1,0]
	v_pk_mul_f32 v[80:81], v[80:81], v[134:135]
	v_cvt_f32_f16_e32 v134, v194
	v_add_f32_e32 v2, 1.0, v2
	v_rcp_f32_e32 v193, v2
	v_cvt_f32_f16_e32 v2, v178
	v_cvt_f32_f16_sdwa v135, v194 dst_sel:DWORD dst_unused:UNUSED_PAD src0_sel:WORD_1
	v_mul_f32_e32 v134, 0xbfb8aa3b, v134
	v_pk_mul_f32 v[138:139], v[176:177], v[192:193]
	v_mul_f32_e32 v2, 0xbfb8aa3b, v2
	v_exp_f32_e32 v2, v2
	v_pk_mul_f32 v[82:83], v[82:83], v[138:139]
	v_mul_f32_e32 v135, 0xbfb8aa3b, v135
	v_exp_f32_e32 v134, v134
	v_add_f32_e32 v2, 1.0, v2
	v_rcp_f32_e32 v138, v2
	v_cvt_f32_f16_sdwa v2, v178 dst_sel:DWORD dst_unused:UNUSED_PAD src0_sel:WORD_1
	v_exp_f32_e32 v135, v135
	v_mul_f32_e32 v167, 0xbfb8aa3b, v167
	v_exp_f32_e32 v176, v167
	v_mul_f32_e32 v2, 0xbfb8aa3b, v2
	v_exp_f32_e32 v2, v2
	v_pk_add_f32 v[134:135], v[134:135], 1.0 op_sel_hi:[1,0]
	v_cvt_f32_f16_sdwa v167, v195 dst_sel:DWORD dst_unused:UNUSED_PAD src0_sel:WORD_1
	v_add_f32_e32 v2, 1.0, v2
	v_rcp_f32_e32 v139, v2
	v_cvt_f32_f16_e32 v2, v179
	v_mul_f32_e32 v167, 0xbfb8aa3b, v167
	v_exp_f32_e32 v177, v167
	v_pk_mul_f32 v[134:135], v[134:135], v[138:139]
	v_mul_f32_e32 v2, 0xbfb8aa3b, v2
	v_pk_mul_f32 v[76:77], v[76:77], v[134:135]
	v_mov_b32_e32 v132, v204
	v_mov_b32_e32 v133, v205
	v_mov_b32_e32 v134, v206
	v_mov_b32_e32 v135, v207
	v_exp_f32_e32 v2, v2
	v_pk_add_f32 v[176:177], v[176:177], 1.0 op_sel_hi:[1,0]
	v_add_f32_e32 v2, 1.0, v2
	v_rcp_f32_e32 v178, v2
	v_cvt_f32_f16_sdwa v2, v179 dst_sel:DWORD dst_unused:UNUSED_PAD src0_sel:WORD_1
	v_mul_f32_e32 v2, 0xbfb8aa3b, v2
	v_exp_f32_e32 v2, v2
	s_nop 0
	v_add_f32_e32 v2, 1.0, v2
	v_rcp_f32_e32 v179, v2
	s_nop 0
	v_pk_mul_f32 v[138:139], v[176:177], v[178:179]
	s_nop 0
	v_pk_mul_f32 v[78:79], v[78:79], v[138:139]
	v_mov_b32_e32 v136, v208
	v_mov_b32_e32 v137, v209
	v_mov_b32_e32 v138, v210
	v_mov_b32_e32 v139, v211
	v_add_co_u32_e32 v244, vcc, 0x4b6000, v0
	s_nop 1
	v_addc_co_u32_e32 v245, vcc, 0, v1, vcc
	global_load_dwordx4 v[196:199], v[244:245], off offset:-2048
	global_load_dwordx4 v[200:203], v[244:245], off offset:2048
	global_load_dwordx4 v[204:207], v[244:245], off offset:-1792
	global_load_dwordx4 v[208:211], v[244:245], off offset:2304
	s_nop 0
	v_cvt_f32_f16_e32 v2, v132
	v_mul_f32_e32 v2, 0xbfb8aa3b, v2
	v_exp_f32_e32 v2, v2
	v_cvt_f32_f16_e32 v167, v136
	v_add_f32_e32 v2, 1.0, v2
	v_rcp_f32_e32 v178, v2
	v_cvt_f32_f16_sdwa v2, v132 dst_sel:DWORD dst_unused:UNUSED_PAD src0_sel:WORD_1
	v_cvt_f32_f16_sdwa v132, v136 dst_sel:DWORD dst_unused:UNUSED_PAD src0_sel:WORD_1
	v_mul_f32_e32 v167, 0xbfb8aa3b, v167
	v_exp_f32_e32 v176, v167
	v_mul_f32_e32 v2, 0xbfb8aa3b, v2
	v_exp_f32_e32 v2, v2
	v_mul_f32_e32 v132, 0xbfb8aa3b, v132
	v_exp_f32_e32 v177, v132
	v_cvt_f32_f16_e32 v132, v137
	v_add_f32_e32 v2, 1.0, v2
	v_rcp_f32_e32 v179, v2
	v_cvt_f32_f16_e32 v2, v133
	v_mul_f32_e32 v132, 0xbfb8aa3b, v132
	v_exp_f32_e32 v132, v132
	v_pk_add_f32 v[176:177], v[176:177], 1.0 op_sel_hi:[1,0]
	v_mul_f32_e32 v2, 0xbfb8aa3b, v2
	v_exp_f32_e32 v2, v2
	v_pk_mul_f32 v[176:177], v[176:177], v[178:179]
	v_add_f32_e32 v2, 1.0, v2
	v_rcp_f32_e32 v136, v2
	v_cvt_f32_f16_sdwa v2, v133 dst_sel:DWORD dst_unused:UNUSED_PAD src0_sel:WORD_1
	v_cvt_f32_f16_sdwa v133, v137 dst_sel:DWORD dst_unused:UNUSED_PAD src0_sel:WORD_1
	v_pk_mul_f32 v[72:73], v[72:73], v[176:177]
	v_mul_f32_e32 v2, 0xbfb8aa3b, v2
	v_exp_f32_e32 v2, v2
	v_mul_f32_e32 v133, 0xbfb8aa3b, v133
	v_exp_f32_e32 v133, v133
	v_add_f32_e32 v2, 1.0, v2
	v_rcp_f32_e32 v137, v2
	v_cvt_f32_f16_e32 v2, v134
	v_pk_add_f32 v[132:133], v[132:133], 1.0 op_sel_hi:[1,0]
	v_mul_f32_e32 v2, 0xbfb8aa3b, v2
	v_exp_f32_e32 v2, v2
	v_pk_mul_f32 v[132:133], v[132:133], v[136:137]
	v_add_f32_e32 v2, 1.0, v2
	v_rcp_f32_e32 v136, v2
	v_cvt_f32_f16_sdwa v2, v134 dst_sel:DWORD dst_unused:UNUSED_PAD src0_sel:WORD_1
	v_pk_mul_f32 v[74:75], v[74:75], v[132:133]
	v_cvt_f32_f16_e32 v132, v138
	v_cvt_f32_f16_sdwa v133, v138 dst_sel:DWORD dst_unused:UNUSED_PAD src0_sel:WORD_1
	v_mul_f32_e32 v2, 0xbfb8aa3b, v2
	v_exp_f32_e32 v2, v2
	v_cvt_f32_f16_e32 v134, v139
	v_mul_f32_e32 v132, 0xbfb8aa3b, v132
	v_mul_f32_e32 v133, 0xbfb8aa3b, v133
	v_add_f32_e32 v2, 1.0, v2
	v_rcp_f32_e32 v137, v2
	v_cvt_f32_f16_e32 v2, v135
	v_mul_f32_e32 v134, 0xbfb8aa3b, v134
	v_exp_f32_e32 v132, v132
	v_exp_f32_e32 v133, v133
	v_mul_f32_e32 v2, 0xbfb8aa3b, v2
	v_exp_f32_e32 v2, v2
	v_exp_f32_e32 v134, v134
	v_pk_add_f32 v[132:133], v[132:133], 1.0 op_sel_hi:[1,0]
	v_add_f32_e32 v2, 1.0, v2
	v_rcp_f32_e32 v138, v2
	v_cvt_f32_f16_sdwa v2, v135 dst_sel:DWORD dst_unused:UNUSED_PAD src0_sel:WORD_1
	v_cvt_f32_f16_sdwa v135, v139 dst_sel:DWORD dst_unused:UNUSED_PAD src0_sel:WORD_1
	v_pk_mul_f32 v[132:133], v[132:133], v[136:137]
	v_mul_f32_e32 v2, 0xbfb8aa3b, v2
	v_exp_f32_e32 v2, v2
	v_mul_f32_e32 v135, 0xbfb8aa3b, v135
	v_exp_f32_e32 v135, v135
	v_pk_mul_f32 v[68:69], v[68:69], v[132:133]
	v_add_f32_e32 v2, 1.0, v2
	v_rcp_f32_e32 v139, v2
	v_pk_add_f32 v[134:135], v[134:135], 1.0 op_sel_hi:[1,0]
	s_nop 0
	v_pk_mul_f32 v[134:135], v[134:135], v[138:139]
	s_nop 0
	v_pk_mul_f32 v[70:71], v[70:71], v[134:135]
	s_mov_b32 s14, 0x3c5000
	v_add_co_u32_e32 v132, vcc, s14, v0
	s_mov_b32 s14, 0x3c6000
	s_nop 0
	v_addc_co_u32_e32 v133, vcc, 0, v1, vcc
	s_waitcnt vmcnt(8)
; __device__ __forceinline__ float ex2(float x) { return __builtin_amdgcn_exp2f(x); }
;     __device__ __forceinline__ void mid(f32x4 (&acc)[2][2][4][2], const pg8::Unit& u, int wr, int wc, int fr, int fq) const {
;         const int row0 = u.pm * 256 + wr * 64 + fr, col0 = u.pn * 256 + wc * 32 + 8 * fq;
;         unsigned base = (unsigned)(row0 * NIN + col0);
;         asm volatile("" : "+v"(base));
;         const half_t* bp0 = P + base;
; #pragma unroll
;         for (int ai = 0; ai < 2; ++ai)
; #pragma unroll
;             for (int m = 0; m < 4; ++m) { const half_t* rowp = bp0 + (size_t)(ai * 128 + m * 16) * NIN;
;                 __builtin_amdgcn_sched_barrier(0);
; #pragma unroll
;                 for (int bj = 0; bj < 2; ++bj) { const h8 ga = *(const h8*)(rowp + C_MR + bj * 128), gb = *(const h8*)(rowp + C_MS + bj * 128);
; #pragma unroll
;                     for (int n = 0; n < 2; ++n)
; #pragma unroll
;                         for (int i = 0; i < 4; ++i) { const float a = (float)ga[4 * n + i], b = (float)gb[4 * n + i];
;                             acc[ai][bj][m][n][i] *= (1.f + ex2(b * -1.44269504f)) * __builtin_amdgcn_rcpf(1.f + ex2(a * -1.44269504f)); } } }
	v_mov_b32_e32 v176, v212
	v_mov_b32_e32 v177, v213
	v_mov_b32_e32 v178, v214
	v_mov_b32_e32 v179, v215
	v_add_co_u32_e32 v136, vcc, s14, v0
	s_nop 1
	v_addc_co_u32_e32 v137, vcc, 0, v1, vcc
	v_mov_b32_e32 v192, v216
	v_mov_b32_e32 v193, v217
	v_mov_b32_e32 v194, v218
	v_mov_b32_e32 v195, v219
	s_nop 0
	v_cvt_f32_f16_e32 v2, v176
	v_mul_f32_e32 v2, 0xbfb8aa3b, v2
	v_exp_f32_e32 v2, v2
	v_cvt_f32_f16_e32 v134, v192
	v_cvt_f32_f16_sdwa v135, v192 dst_sel:DWORD dst_unused:UNUSED_PAD src0_sel:WORD_1
	v_cvt_f32_f16_e32 v167, v193
	v_add_f32_e32 v2, 1.0, v2
	v_rcp_f32_e32 v138, v2
	v_cvt_f32_f16_sdwa v2, v176 dst_sel:DWORD dst_unused:UNUSED_PAD src0_sel:WORD_1
	v_mul_f32_e32 v167, 0xbfb8aa3b, v167
	v_exp_f32_e32 v176, v167
	v_cvt_f32_f16_sdwa v167, v193 dst_sel:DWORD dst_unused:UNUSED_PAD src0_sel:WORD_1
	v_mul_f32_e32 v2, 0xbfb8aa3b, v2
	v_exp_f32_e32 v2, v2
	v_mul_f32_e32 v134, 0xbfb8aa3b, v134
	v_mul_f32_e32 v135, 0xbfb8aa3b, v135
	v_mul_f32_e32 v167, 0xbfb8aa3b, v167
	v_add_f32_e32 v2, 1.0, v2
	v_rcp_f32_e32 v139, v2
	v_cvt_f32_f16_e32 v2, v177
	v_exp_f32_e32 v134, v134
	v_exp_f32_e32 v135, v135
	v_mul_f32_e32 v2, 0xbfb8aa3b, v2
	v_exp_f32_e32 v2, v2
	v_pk_add_f32 v[134:135], v[134:135], 1.0 op_sel_hi:[1,0]
	v_add_f32_e32 v2, 1.0, v2
	v_rcp_f32_e32 v192, v2
	v_cvt_f32_f16_sdwa v2, v177 dst_sel:DWORD dst_unused:UNUSED_PAD src0_sel:WORD_1
	v_exp_f32_e32 v177, v167
	v_pk_mul_f32 v[134:135], v[134:135], v[138:139]
	v_cvt_f32_f16_e32 v167, v195
	v_mul_f32_e32 v2, 0xbfb8aa3b, v2
	v_exp_f32_e32 v2, v2
	v_pk_add_f32 v[176:177], v[176:177], 1.0 op_sel_hi:[1,0]
	v_pk_mul_f32 v[64:65], v[64:65], v[134:135]
	v_cvt_f32_f16_e32 v134, v194
	v_add_f32_e32 v2, 1.0, v2
	v_rcp_f32_e32 v193, v2
	v_cvt_f32_f16_e32 v2, v178
	v_cvt_f32_f16_sdwa v135, v194 dst_sel:DWORD dst_unused:UNUSED_PAD src0_sel:WORD_1
	v_mul_f32_e32 v134, 0xbfb8aa3b, v134
	v_pk_mul_f32 v[138:139], v[176:177], v[192:193]
	v_mul_f32_e32 v2, 0xbfb8aa3b, v2
	v_exp_f32_e32 v2, v2
	v_pk_mul_f32 v[66:67], v[66:67], v[138:139]
	v_mul_f32_e32 v135, 0xbfb8aa3b, v135
	v_exp_f32_e32 v134, v134
	v_add_f32_e32 v2, 1.0, v2
	v_rcp_f32_e32 v138, v2
	v_cvt_f32_f16_sdwa v2, v178 dst_sel:DWORD dst_unused:UNUSED_PAD src0_sel:WORD_1
	v_exp_f32_e32 v135, v135
	v_mul_f32_e32 v167, 0xbfb8aa3b, v167
	v_exp_f32_e32 v176, v167
	v_mul_f32_e32 v2, 0xbfb8aa3b, v2
	v_exp_f32_e32 v2, v2
	v_pk_add_f32 v[134:135], v[134:135], 1.0 op_sel_hi:[1,0]
	v_cvt_f32_f16_sdwa v167, v195 dst_sel:DWORD dst_unused:UNUSED_PAD src0_sel:WORD_1
	v_add_f32_e32 v2, 1.0, v2
	v_rcp_f32_e32 v139, v2
	v_cvt_f32_f16_e32 v2, v179
	v_mul_f32_e32 v167, 0xbfb8aa3b, v167
	v_exp_f32_e32 v177, v167
	v_pk_mul_f32 v[134:135], v[134:135], v[138:139]
	v_mul_f32_e32 v2, 0xbfb8aa3b, v2
	v_pk_mul_f32 v[60:61], v[60:61], v[134:135]
	v_mov_b32_e32 v132, v220
	v_mov_b32_e32 v133, v221
	v_mov_b32_e32 v134, v222
	v_mov_b32_e32 v135, v223
	v_exp_f32_e32 v2, v2
	v_pk_add_f32 v[176:177], v[176:177], 1.0 op_sel_hi:[1,0]
	v_add_f32_e32 v2, 1.0, v2
	v_rcp_f32_e32 v178, v2
	v_cvt_f32_f16_sdwa v2, v179 dst_sel:DWORD dst_unused:UNUSED_PAD src0_sel:WORD_1
	v_mul_f32_e32 v2, 0xbfb8aa3b, v2
	v_exp_f32_e32 v2, v2
	s_nop 0
	v_add_f32_e32 v2, 1.0, v2
	v_rcp_f32_e32 v179, v2
	s_nop 0
	v_pk_mul_f32 v[138:139], v[176:177], v[178:179]
	s_nop 0
	v_pk_mul_f32 v[62:63], v[62:63], v[138:139]
	v_mov_b32_e32 v136, v224
	v_mov_b32_e32 v137, v225
	v_mov_b32_e32 v138, v226
	v_mov_b32_e32 v139, v227
	v_add_co_u32_e32 v244, vcc, 0x52e000, v0
	s_nop 1
	v_addc_co_u32_e32 v245, vcc, 0, v1, vcc
	global_load_dwordx4 v[212:215], v[244:245], off offset:-2048
	global_load_dwordx4 v[216:219], v[244:245], off offset:2048
	global_load_dwordx4 v[220:223], v[244:245], off offset:-1792
	global_load_dwordx4 v[224:227], v[244:245], off offset:2304
	s_nop 0
	v_cvt_f32_f16_e32 v2, v132
	v_mul_f32_e32 v2, 0xbfb8aa3b, v2
	v_exp_f32_e32 v2, v2
	v_cvt_f32_f16_e32 v167, v136
	v_add_f32_e32 v2, 1.0, v2
	v_rcp_f32_e32 v178, v2
	v_cvt_f32_f16_sdwa v2, v132 dst_sel:DWORD dst_unused:UNUSED_PAD src0_sel:WORD_1
	v_cvt_f32_f16_sdwa v132, v136 dst_sel:DWORD dst_unused:UNUSED_PAD src0_sel:WORD_1
	v_mul_f32_e32 v167, 0xbfb8aa3b, v167
	v_exp_f32_e32 v176, v167
	v_mul_f32_e32 v2, 0xbfb8aa3b, v2
	v_exp_f32_e32 v2, v2
	v_mul_f32_e32 v132, 0xbfb8aa3b, v132
	v_exp_f32_e32 v177, v132
	v_cvt_f32_f16_e32 v132, v137
	v_add_f32_e32 v2, 1.0, v2
	v_rcp_f32_e32 v179, v2
	v_cvt_f32_f16_e32 v2, v133
	v_mul_f32_e32 v132, 0xbfb8aa3b, v132
	v_exp_f32_e32 v132, v132
	v_pk_add_f32 v[176:177], v[176:177], 1.0 op_sel_hi:[1,0]
	v_mul_f32_e32 v2, 0xbfb8aa3b, v2
	v_exp_f32_e32 v2, v2
	v_pk_mul_f32 v[176:177], v[176:177], v[178:179]
	v_add_f32_e32 v2, 1.0, v2
	v_rcp_f32_e32 v136, v2
	v_cvt_f32_f16_sdwa v2, v133 dst_sel:DWORD dst_unused:UNUSED_PAD src0_sel:WORD_1
	v_cvt_f32_f16_sdwa v133, v137 dst_sel:DWORD dst_unused:UNUSED_PAD src0_sel:WORD_1
	v_pk_mul_f32 v[56:57], v[56:57], v[176:177]
	v_mul_f32_e32 v2, 0xbfb8aa3b, v2
	v_exp_f32_e32 v2, v2
	v_mul_f32_e32 v133, 0xbfb8aa3b, v133
	v_exp_f32_e32 v133, v133
	v_add_f32_e32 v2, 1.0, v2
	v_rcp_f32_e32 v137, v2
	v_cvt_f32_f16_e32 v2, v134
	v_pk_add_f32 v[132:133], v[132:133], 1.0 op_sel_hi:[1,0]
	v_mul_f32_e32 v2, 0xbfb8aa3b, v2
	v_exp_f32_e32 v2, v2
	v_pk_mul_f32 v[132:133], v[132:133], v[136:137]
	v_add_f32_e32 v2, 1.0, v2
	v_rcp_f32_e32 v136, v2
	v_cvt_f32_f16_sdwa v2, v134 dst_sel:DWORD dst_unused:UNUSED_PAD src0_sel:WORD_1
	v_pk_mul_f32 v[58:59], v[58:59], v[132:133]
	v_cvt_f32_f16_e32 v132, v138
	v_cvt_f32_f16_sdwa v133, v138 dst_sel:DWORD dst_unused:UNUSED_PAD src0_sel:WORD_1
	v_mul_f32_e32 v2, 0xbfb8aa3b, v2
	v_exp_f32_e32 v2, v2
	v_cvt_f32_f16_e32 v134, v139
	v_mul_f32_e32 v132, 0xbfb8aa3b, v132
	v_mul_f32_e32 v133, 0xbfb8aa3b, v133
	v_add_f32_e32 v2, 1.0, v2
	v_rcp_f32_e32 v137, v2
	v_cvt_f32_f16_e32 v2, v135
	v_mul_f32_e32 v134, 0xbfb8aa3b, v134
	v_exp_f32_e32 v132, v132
	v_exp_f32_e32 v133, v133
	v_mul_f32_e32 v2, 0xbfb8aa3b, v2
	v_exp_f32_e32 v2, v2
	v_exp_f32_e32 v134, v134
	v_pk_add_f32 v[132:133], v[132:133], 1.0 op_sel_hi:[1,0]
	v_add_f32_e32 v2, 1.0, v2
	v_rcp_f32_e32 v138, v2
	v_cvt_f32_f16_sdwa v2, v135 dst_sel:DWORD dst_unused:UNUSED_PAD src0_sel:WORD_1
	v_cvt_f32_f16_sdwa v135, v139 dst_sel:DWORD dst_unused:UNUSED_PAD src0_sel:WORD_1
	v_pk_mul_f32 v[132:133], v[132:133], v[136:137]
	v_mul_f32_e32 v2, 0xbfb8aa3b, v2
	v_exp_f32_e32 v2, v2
	v_mul_f32_e32 v135, 0xbfb8aa3b, v135
	v_exp_f32_e32 v135, v135
	v_pk_mul_f32 v[52:53], v[52:53], v[132:133]
	v_add_f32_e32 v2, 1.0, v2
	v_rcp_f32_e32 v139, v2
	v_pk_add_f32 v[134:135], v[134:135], 1.0 op_sel_hi:[1,0]
	s_nop 0
	v_pk_mul_f32 v[134:135], v[134:135], v[138:139]
	s_nop 0
	v_pk_mul_f32 v[54:55], v[54:55], v[134:135]
	s_mov_b32 s14, 0x43d000
	v_add_co_u32_e32 v132, vcc, s14, v0
	s_mov_b32 s14, 0x43e000
	s_nop 0
	v_addc_co_u32_e32 v133, vcc, 0, v1, vcc
	s_waitcnt vmcnt(8)
; __device__ __forceinline__ float ex2(float x) { return __builtin_amdgcn_exp2f(x); }
;     __device__ __forceinline__ void mid(f32x4 (&acc)[2][2][4][2], const pg8::Unit& u, int wr, int wc, int fr, int fq) const {
;         const int row0 = u.pm * 256 + wr * 64 + fr, col0 = u.pn * 256 + wc * 32 + 8 * fq;
;         unsigned base = (unsigned)(row0 * NIN + col0);
;         asm volatile("" : "+v"(base));
;         const half_t* bp0 = P + base;
; #pragma unroll
;         for (int ai = 0; ai < 2; ++ai)
; #pragma unroll
;             for (int m = 0; m < 4; ++m) { const half_t* rowp = bp0 + (size_t)(ai * 128 + m * 16) * NIN;
;                 __builtin_amdgcn_sched_barrier(0);
; #pragma unroll
;                 for (int bj = 0; bj < 2; ++bj) { const h8 ga = *(const h8*)(rowp + C_MR + bj * 128), gb = *(const h8*)(rowp + C_MS + bj * 128);
; #pragma unroll
;                     for (int n = 0; n < 2; ++n)
; #pragma unroll
;                         for (int i = 0; i < 4; ++i) { const float a = (float)ga[4 * n + i], b = (float)gb[4 * n + i];
;                             acc[ai][bj][m][n][i] *= (1.f + ex2(b * -1.44269504f)) * __builtin_amdgcn_rcpf(1.f + ex2(a * -1.44269504f)); } } }
	v_mov_b32_e32 v176, v228
	v_mov_b32_e32 v177, v229
	v_mov_b32_e32 v178, v230
	v_mov_b32_e32 v179, v231
	v_add_co_u32_e32 v136, vcc, s14, v0
	s_nop 1
	v_addc_co_u32_e32 v137, vcc, 0, v1, vcc
	v_mov_b32_e32 v192, v232
	v_mov_b32_e32 v193, v233
	v_mov_b32_e32 v194, v234
	v_mov_b32_e32 v195, v235
	s_nop 0
	v_cvt_f32_f16_e32 v2, v176
	v_mul_f32_e32 v2, 0xbfb8aa3b, v2
	v_exp_f32_e32 v2, v2
	v_cvt_f32_f16_e32 v134, v192
	v_cvt_f32_f16_sdwa v135, v192 dst_sel:DWORD dst_unused:UNUSED_PAD src0_sel:WORD_1
	v_cvt_f32_f16_e32 v167, v193
	v_add_f32_e32 v2, 1.0, v2
	v_rcp_f32_e32 v138, v2
	v_cvt_f32_f16_sdwa v2, v176 dst_sel:DWORD dst_unused:UNUSED_PAD src0_sel:WORD_1
	v_mul_f32_e32 v167, 0xbfb8aa3b, v167
	v_exp_f32_e32 v176, v167
	v_cvt_f32_f16_sdwa v167, v193 dst_sel:DWORD dst_unused:UNUSED_PAD src0_sel:WORD_1
	v_mul_f32_e32 v2, 0xbfb8aa3b, v2
	v_exp_f32_e32 v2, v2
	v_mul_f32_e32 v134, 0xbfb8aa3b, v134
	v_mul_f32_e32 v135, 0xbfb8aa3b, v135
	v_mul_f32_e32 v167, 0xbfb8aa3b, v167
	v_add_f32_e32 v2, 1.0, v2
	v_rcp_f32_e32 v139, v2
	v_cvt_f32_f16_e32 v2, v177
	v_exp_f32_e32 v134, v134
	v_exp_f32_e32 v135, v135
	v_mul_f32_e32 v2, 0xbfb8aa3b, v2
	v_exp_f32_e32 v2, v2
	v_pk_add_f32 v[134:135], v[134:135], 1.0 op_sel_hi:[1,0]
	v_add_f32_e32 v2, 1.0, v2
	v_rcp_f32_e32 v192, v2
	v_cvt_f32_f16_sdwa v2, v177 dst_sel:DWORD dst_unused:UNUSED_PAD src0_sel:WORD_1
	v_exp_f32_e32 v177, v167
	v_pk_mul_f32 v[134:135], v[134:135], v[138:139]
	v_cvt_f32_f16_e32 v167, v195
	v_mul_f32_e32 v2, 0xbfb8aa3b, v2
	v_exp_f32_e32 v2, v2
	v_pk_add_f32 v[176:177], v[176:177], 1.0 op_sel_hi:[1,0]
	v_pk_mul_f32 v[48:49], v[48:49], v[134:135]
	v_cvt_f32_f16_e32 v134, v194
	v_add_f32_e32 v2, 1.0, v2
	v_rcp_f32_e32 v193, v2
	v_cvt_f32_f16_e32 v2, v178
	v_cvt_f32_f16_sdwa v135, v194 dst_sel:DWORD dst_unused:UNUSED_PAD src0_sel:WORD_1
	v_mul_f32_e32 v134, 0xbfb8aa3b, v134
	v_pk_mul_f32 v[138:139], v[176:177], v[192:193]
	v_mul_f32_e32 v2, 0xbfb8aa3b, v2
	v_exp_f32_e32 v2, v2
	v_pk_mul_f32 v[50:51], v[50:51], v[138:139]
	v_mul_f32_e32 v135, 0xbfb8aa3b, v135
	v_exp_f32_e32 v134, v134
	v_add_f32_e32 v2, 1.0, v2
	v_rcp_f32_e32 v138, v2
	v_cvt_f32_f16_sdwa v2, v178 dst_sel:DWORD dst_unused:UNUSED_PAD src0_sel:WORD_1
	v_exp_f32_e32 v135, v135
	v_mul_f32_e32 v167, 0xbfb8aa3b, v167
	v_exp_f32_e32 v176, v167
	v_mul_f32_e32 v2, 0xbfb8aa3b, v2
	v_exp_f32_e32 v2, v2
	v_pk_add_f32 v[134:135], v[134:135], 1.0 op_sel_hi:[1,0]
	v_cvt_f32_f16_sdwa v167, v195 dst_sel:DWORD dst_unused:UNUSED_PAD src0_sel:WORD_1
	v_add_f32_e32 v2, 1.0, v2
	v_rcp_f32_e32 v139, v2
	v_cvt_f32_f16_e32 v2, v179
	v_mul_f32_e32 v167, 0xbfb8aa3b, v167
	v_exp_f32_e32 v177, v167
	v_pk_mul_f32 v[134:135], v[134:135], v[138:139]
	v_mul_f32_e32 v2, 0xbfb8aa3b, v2
	v_pk_mul_f32 v[44:45], v[44:45], v[134:135]
	v_mov_b32_e32 v132, v236
	v_mov_b32_e32 v133, v237
	v_mov_b32_e32 v134, v238
	v_mov_b32_e32 v135, v239
	v_exp_f32_e32 v2, v2
	v_pk_add_f32 v[176:177], v[176:177], 1.0 op_sel_hi:[1,0]
	v_add_f32_e32 v2, 1.0, v2
	v_rcp_f32_e32 v178, v2
	v_cvt_f32_f16_sdwa v2, v179 dst_sel:DWORD dst_unused:UNUSED_PAD src0_sel:WORD_1
	v_mul_f32_e32 v2, 0xbfb8aa3b, v2
	v_exp_f32_e32 v2, v2
	s_nop 0
	v_add_f32_e32 v2, 1.0, v2
	v_rcp_f32_e32 v179, v2
	s_nop 0
	v_pk_mul_f32 v[138:139], v[176:177], v[178:179]
	s_nop 0
	v_pk_mul_f32 v[46:47], v[46:47], v[138:139]
	v_mov_b32_e32 v136, v240
	v_mov_b32_e32 v137, v241
	v_mov_b32_e32 v138, v242
	v_mov_b32_e32 v139, v243
	s_nop 0
	v_cvt_f32_f16_e32 v2, v132
	v_mul_f32_e32 v2, 0xbfb8aa3b, v2
	v_exp_f32_e32 v2, v2
	v_cvt_f32_f16_e32 v167, v136
	v_add_f32_e32 v2, 1.0, v2
	v_rcp_f32_e32 v178, v2
	v_cvt_f32_f16_sdwa v2, v132 dst_sel:DWORD dst_unused:UNUSED_PAD src0_sel:WORD_1
	v_cvt_f32_f16_sdwa v132, v136 dst_sel:DWORD dst_unused:UNUSED_PAD src0_sel:WORD_1
	v_mul_f32_e32 v167, 0xbfb8aa3b, v167
	v_exp_f32_e32 v176, v167
	v_mul_f32_e32 v2, 0xbfb8aa3b, v2
	v_exp_f32_e32 v2, v2
	v_mul_f32_e32 v132, 0xbfb8aa3b, v132
	v_exp_f32_e32 v177, v132
	v_cvt_f32_f16_e32 v132, v137
	v_add_f32_e32 v2, 1.0, v2
	v_rcp_f32_e32 v179, v2
	v_cvt_f32_f16_e32 v2, v133
	v_mul_f32_e32 v132, 0xbfb8aa3b, v132
	v_exp_f32_e32 v132, v132
	v_pk_add_f32 v[176:177], v[176:177], 1.0 op_sel_hi:[1,0]
	v_mul_f32_e32 v2, 0xbfb8aa3b, v2
	v_exp_f32_e32 v2, v2
	v_pk_mul_f32 v[176:177], v[176:177], v[178:179]
	v_add_f32_e32 v2, 1.0, v2
	v_rcp_f32_e32 v136, v2
	v_cvt_f32_f16_sdwa v2, v133 dst_sel:DWORD dst_unused:UNUSED_PAD src0_sel:WORD_1
	v_cvt_f32_f16_sdwa v133, v137 dst_sel:DWORD dst_unused:UNUSED_PAD src0_sel:WORD_1
	v_pk_mul_f32 v[40:41], v[40:41], v[176:177]
	v_mul_f32_e32 v2, 0xbfb8aa3b, v2
	v_exp_f32_e32 v2, v2
	v_mul_f32_e32 v133, 0xbfb8aa3b, v133
	v_exp_f32_e32 v133, v133
	v_add_f32_e32 v2, 1.0, v2
	v_rcp_f32_e32 v137, v2
	v_cvt_f32_f16_e32 v2, v134
	v_pk_add_f32 v[132:133], v[132:133], 1.0 op_sel_hi:[1,0]
	v_mul_f32_e32 v2, 0xbfb8aa3b, v2
	v_exp_f32_e32 v2, v2
	v_pk_mul_f32 v[132:133], v[132:133], v[136:137]
	v_add_f32_e32 v2, 1.0, v2
	v_rcp_f32_e32 v136, v2
	v_cvt_f32_f16_sdwa v2, v134 dst_sel:DWORD dst_unused:UNUSED_PAD src0_sel:WORD_1
	v_pk_mul_f32 v[42:43], v[42:43], v[132:133]
	v_cvt_f32_f16_e32 v132, v138
	v_cvt_f32_f16_sdwa v133, v138 dst_sel:DWORD dst_unused:UNUSED_PAD src0_sel:WORD_1
	v_mul_f32_e32 v2, 0xbfb8aa3b, v2
	v_exp_f32_e32 v2, v2
	v_cvt_f32_f16_e32 v134, v139
	v_mul_f32_e32 v132, 0xbfb8aa3b, v132
	v_mul_f32_e32 v133, 0xbfb8aa3b, v133
	v_add_f32_e32 v2, 1.0, v2
	v_rcp_f32_e32 v137, v2
	v_cvt_f32_f16_e32 v2, v135
	v_mul_f32_e32 v134, 0xbfb8aa3b, v134
	v_exp_f32_e32 v132, v132
	v_exp_f32_e32 v133, v133
	v_mul_f32_e32 v2, 0xbfb8aa3b, v2
	v_exp_f32_e32 v2, v2
	v_exp_f32_e32 v134, v134
	v_pk_add_f32 v[132:133], v[132:133], 1.0 op_sel_hi:[1,0]
	v_add_f32_e32 v2, 1.0, v2
	v_rcp_f32_e32 v138, v2
	v_cvt_f32_f16_sdwa v2, v135 dst_sel:DWORD dst_unused:UNUSED_PAD src0_sel:WORD_1
	v_cvt_f32_f16_sdwa v135, v139 dst_sel:DWORD dst_unused:UNUSED_PAD src0_sel:WORD_1
	v_pk_mul_f32 v[132:133], v[132:133], v[136:137]
	v_mul_f32_e32 v2, 0xbfb8aa3b, v2
	v_exp_f32_e32 v2, v2
	v_mul_f32_e32 v135, 0xbfb8aa3b, v135
	v_exp_f32_e32 v135, v135
	v_pk_mul_f32 v[36:37], v[36:37], v[132:133]
	v_add_f32_e32 v2, 1.0, v2
	v_rcp_f32_e32 v139, v2
	v_pk_add_f32 v[134:135], v[134:135], 1.0 op_sel_hi:[1,0]
	s_nop 0
	v_pk_mul_f32 v[134:135], v[134:135], v[138:139]
	s_nop 0
	v_pk_mul_f32 v[38:39], v[38:39], v[134:135]
	s_mov_b32 s14, 0x4b5000
	v_add_co_u32_e32 v132, vcc, s14, v0
	s_mov_b32 s14, 0x4b6000
	s_nop 0
	v_addc_co_u32_e32 v133, vcc, 0, v1, vcc
	s_waitcnt vmcnt(4)
; __device__ __forceinline__ float ex2(float x) { return __builtin_amdgcn_exp2f(x); }
;     __device__ __forceinline__ void mid(f32x4 (&acc)[2][2][4][2], const pg8::Unit& u, int wr, int wc, int fr, int fq) const {
;         const int row0 = u.pm * 256 + wr * 64 + fr, col0 = u.pn * 256 + wc * 32 + 8 * fq;
;         unsigned base = (unsigned)(row0 * NIN + col0);
;         asm volatile("" : "+v"(base));
;         const half_t* bp0 = P + base;
; #pragma unroll
;         for (int ai = 0; ai < 2; ++ai)
; #pragma unroll
;             for (int m = 0; m < 4; ++m) { const half_t* rowp = bp0 + (size_t)(ai * 128 + m * 16) * NIN;
;                 __builtin_amdgcn_sched_barrier(0);
; #pragma unroll
;                 for (int bj = 0; bj < 2; ++bj) { const h8 ga = *(const h8*)(rowp + C_MR + bj * 128), gb = *(const h8*)(rowp + C_MS + bj * 128);
; #pragma unroll
;                     for (int n = 0; n < 2; ++n)
; #pragma unroll
;                         for (int i = 0; i < 4; ++i) { const float a = (float)ga[4 * n + i], b = (float)gb[4 * n + i];
;                             acc[ai][bj][m][n][i] *= (1.f + ex2(b * -1.44269504f)) * __builtin_amdgcn_rcpf(1.f + ex2(a * -1.44269504f)); } } }
	v_mov_b32_e32 v176, v196
	v_mov_b32_e32 v177, v197
	v_mov_b32_e32 v178, v198
	v_mov_b32_e32 v179, v199
	v_add_co_u32_e32 v136, vcc, s14, v0
	s_nop 1
	v_addc_co_u32_e32 v137, vcc, 0, v1, vcc
	v_mov_b32_e32 v192, v200
	v_mov_b32_e32 v193, v201
	v_mov_b32_e32 v194, v202
	v_mov_b32_e32 v195, v203
	s_nop 0
	v_cvt_f32_f16_e32 v2, v176
	v_mul_f32_e32 v2, 0xbfb8aa3b, v2
	v_exp_f32_e32 v2, v2
	v_cvt_f32_f16_e32 v134, v192
	v_cvt_f32_f16_sdwa v135, v192 dst_sel:DWORD dst_unused:UNUSED_PAD src0_sel:WORD_1
	v_cvt_f32_f16_e32 v167, v193
	v_add_f32_e32 v2, 1.0, v2
	v_rcp_f32_e32 v138, v2
	v_cvt_f32_f16_sdwa v2, v176 dst_sel:DWORD dst_unused:UNUSED_PAD src0_sel:WORD_1
	v_mul_f32_e32 v167, 0xbfb8aa3b, v167
	v_exp_f32_e32 v176, v167
	v_cvt_f32_f16_sdwa v167, v193 dst_sel:DWORD dst_unused:UNUSED_PAD src0_sel:WORD_1
	v_mul_f32_e32 v2, 0xbfb8aa3b, v2
	v_exp_f32_e32 v2, v2
	v_mul_f32_e32 v134, 0xbfb8aa3b, v134
	v_mul_f32_e32 v135, 0xbfb8aa3b, v135
	v_mul_f32_e32 v167, 0xbfb8aa3b, v167
	v_add_f32_e32 v2, 1.0, v2
	v_rcp_f32_e32 v139, v2
	v_cvt_f32_f16_e32 v2, v177
	v_exp_f32_e32 v134, v134
	v_exp_f32_e32 v135, v135
	v_mul_f32_e32 v2, 0xbfb8aa3b, v2
	v_exp_f32_e32 v2, v2
	v_pk_add_f32 v[134:135], v[134:135], 1.0 op_sel_hi:[1,0]
	v_add_f32_e32 v2, 1.0, v2
	v_rcp_f32_e32 v192, v2
	v_cvt_f32_f16_sdwa v2, v177 dst_sel:DWORD dst_unused:UNUSED_PAD src0_sel:WORD_1
	v_exp_f32_e32 v177, v167
	v_pk_mul_f32 v[134:135], v[134:135], v[138:139]
	v_cvt_f32_f16_e32 v167, v195
	v_mul_f32_e32 v2, 0xbfb8aa3b, v2
	v_exp_f32_e32 v2, v2
	v_pk_add_f32 v[176:177], v[176:177], 1.0 op_sel_hi:[1,0]
	v_pk_mul_f32 v[32:33], v[32:33], v[134:135]
	v_cvt_f32_f16_e32 v134, v194
	v_add_f32_e32 v2, 1.0, v2
	v_rcp_f32_e32 v193, v2
	v_cvt_f32_f16_e32 v2, v178
	v_cvt_f32_f16_sdwa v135, v194 dst_sel:DWORD dst_unused:UNUSED_PAD src0_sel:WORD_1
	v_mul_f32_e32 v134, 0xbfb8aa3b, v134
	v_pk_mul_f32 v[138:139], v[176:177], v[192:193]
	v_mul_f32_e32 v2, 0xbfb8aa3b, v2
	v_exp_f32_e32 v2, v2
	v_pk_mul_f32 v[34:35], v[34:35], v[138:139]
	v_mul_f32_e32 v135, 0xbfb8aa3b, v135
	v_exp_f32_e32 v134, v134
	v_add_f32_e32 v2, 1.0, v2
	v_rcp_f32_e32 v138, v2
	v_cvt_f32_f16_sdwa v2, v178 dst_sel:DWORD dst_unused:UNUSED_PAD src0_sel:WORD_1
	v_exp_f32_e32 v135, v135
	v_mul_f32_e32 v167, 0xbfb8aa3b, v167
	v_exp_f32_e32 v176, v167
	v_mul_f32_e32 v2, 0xbfb8aa3b, v2
	v_exp_f32_e32 v2, v2
	v_pk_add_f32 v[134:135], v[134:135], 1.0 op_sel_hi:[1,0]
	v_cvt_f32_f16_sdwa v167, v195 dst_sel:DWORD dst_unused:UNUSED_PAD src0_sel:WORD_1
	v_add_f32_e32 v2, 1.0, v2
	v_rcp_f32_e32 v139, v2
	v_cvt_f32_f16_e32 v2, v179
	v_mul_f32_e32 v167, 0xbfb8aa3b, v167
	v_exp_f32_e32 v177, v167
	v_pk_mul_f32 v[134:135], v[134:135], v[138:139]
	v_mul_f32_e32 v2, 0xbfb8aa3b, v2
	v_pk_mul_f32 v[28:29], v[28:29], v[134:135]
	v_mov_b32_e32 v132, v204
	v_mov_b32_e32 v133, v205
	v_mov_b32_e32 v134, v206
	v_mov_b32_e32 v135, v207
	v_exp_f32_e32 v2, v2
	v_pk_add_f32 v[176:177], v[176:177], 1.0 op_sel_hi:[1,0]
	v_add_f32_e32 v2, 1.0, v2
	v_rcp_f32_e32 v178, v2
	v_cvt_f32_f16_sdwa v2, v179 dst_sel:DWORD dst_unused:UNUSED_PAD src0_sel:WORD_1
	v_mul_f32_e32 v2, 0xbfb8aa3b, v2
	v_exp_f32_e32 v2, v2
	s_nop 0
	v_add_f32_e32 v2, 1.0, v2
	v_rcp_f32_e32 v179, v2
	s_nop 0
	v_pk_mul_f32 v[138:139], v[176:177], v[178:179]
	s_nop 0
	v_pk_mul_f32 v[30:31], v[30:31], v[138:139]
	v_mov_b32_e32 v136, v208
	v_mov_b32_e32 v137, v209
	v_mov_b32_e32 v138, v210
	v_mov_b32_e32 v139, v211
	s_nop 0
	v_cvt_f32_f16_e32 v2, v132
	v_mul_f32_e32 v2, 0xbfb8aa3b, v2
	v_exp_f32_e32 v2, v2
	v_cvt_f32_f16_e32 v167, v136
	v_add_f32_e32 v2, 1.0, v2
	v_rcp_f32_e32 v178, v2
	v_cvt_f32_f16_sdwa v2, v132 dst_sel:DWORD dst_unused:UNUSED_PAD src0_sel:WORD_1
	v_cvt_f32_f16_sdwa v132, v136 dst_sel:DWORD dst_unused:UNUSED_PAD src0_sel:WORD_1
	v_mul_f32_e32 v167, 0xbfb8aa3b, v167
	v_exp_f32_e32 v176, v167
	v_mul_f32_e32 v2, 0xbfb8aa3b, v2
	v_exp_f32_e32 v2, v2
	v_mul_f32_e32 v132, 0xbfb8aa3b, v132
	v_exp_f32_e32 v177, v132
	v_cvt_f32_f16_e32 v132, v137
	v_add_f32_e32 v2, 1.0, v2
	v_rcp_f32_e32 v179, v2
	v_cvt_f32_f16_e32 v2, v133
	v_mul_f32_e32 v132, 0xbfb8aa3b, v132
	v_exp_f32_e32 v132, v132
	v_pk_add_f32 v[176:177], v[176:177], 1.0 op_sel_hi:[1,0]
	v_mul_f32_e32 v2, 0xbfb8aa3b, v2
	v_exp_f32_e32 v2, v2
	v_pk_mul_f32 v[176:177], v[176:177], v[178:179]
	v_add_f32_e32 v2, 1.0, v2
	v_rcp_f32_e32 v136, v2
	v_cvt_f32_f16_sdwa v2, v133 dst_sel:DWORD dst_unused:UNUSED_PAD src0_sel:WORD_1
	v_cvt_f32_f16_sdwa v133, v137 dst_sel:DWORD dst_unused:UNUSED_PAD src0_sel:WORD_1
	v_pk_mul_f32 v[24:25], v[24:25], v[176:177]
	v_mul_f32_e32 v2, 0xbfb8aa3b, v2
	v_exp_f32_e32 v2, v2
	v_mul_f32_e32 v133, 0xbfb8aa3b, v133
	v_exp_f32_e32 v133, v133
	v_add_f32_e32 v2, 1.0, v2
	v_rcp_f32_e32 v137, v2
	v_cvt_f32_f16_e32 v2, v134
	v_pk_add_f32 v[132:133], v[132:133], 1.0 op_sel_hi:[1,0]
	v_mul_f32_e32 v2, 0xbfb8aa3b, v2
	v_exp_f32_e32 v2, v2
	v_pk_mul_f32 v[132:133], v[132:133], v[136:137]
	v_add_f32_e32 v2, 1.0, v2
	v_rcp_f32_e32 v136, v2
	v_cvt_f32_f16_sdwa v2, v134 dst_sel:DWORD dst_unused:UNUSED_PAD src0_sel:WORD_1
	v_pk_mul_f32 v[26:27], v[26:27], v[132:133]
	v_cvt_f32_f16_e32 v132, v138
	v_cvt_f32_f16_sdwa v133, v138 dst_sel:DWORD dst_unused:UNUSED_PAD src0_sel:WORD_1
	v_mul_f32_e32 v2, 0xbfb8aa3b, v2
	v_exp_f32_e32 v2, v2
	v_cvt_f32_f16_e32 v134, v139
	v_mul_f32_e32 v132, 0xbfb8aa3b, v132
	v_mul_f32_e32 v133, 0xbfb8aa3b, v133
	v_add_f32_e32 v2, 1.0, v2
	v_rcp_f32_e32 v137, v2
	v_cvt_f32_f16_e32 v2, v135
	v_mul_f32_e32 v134, 0xbfb8aa3b, v134
	v_exp_f32_e32 v132, v132
	v_exp_f32_e32 v133, v133
	v_mul_f32_e32 v2, 0xbfb8aa3b, v2
	v_exp_f32_e32 v2, v2
	v_exp_f32_e32 v134, v134
	v_pk_add_f32 v[132:133], v[132:133], 1.0 op_sel_hi:[1,0]
	v_add_f32_e32 v2, 1.0, v2
	v_rcp_f32_e32 v138, v2
	v_cvt_f32_f16_sdwa v2, v135 dst_sel:DWORD dst_unused:UNUSED_PAD src0_sel:WORD_1
	v_cvt_f32_f16_sdwa v135, v139 dst_sel:DWORD dst_unused:UNUSED_PAD src0_sel:WORD_1
	v_pk_mul_f32 v[132:133], v[132:133], v[136:137]
	v_mul_f32_e32 v2, 0xbfb8aa3b, v2
	v_exp_f32_e32 v2, v2
	v_mul_f32_e32 v135, 0xbfb8aa3b, v135
	v_exp_f32_e32 v135, v135
	v_pk_mul_f32 v[20:21], v[20:21], v[132:133]
	v_add_f32_e32 v2, 1.0, v2
	v_rcp_f32_e32 v139, v2
	v_pk_add_f32 v[134:135], v[134:135], 1.0 op_sel_hi:[1,0]
	s_nop 0
	v_pk_mul_f32 v[134:135], v[134:135], v[138:139]
	s_nop 0
	v_pk_mul_f32 v[22:23], v[22:23], v[134:135]
	s_mov_b32 s14, 0x52d000
	v_add_co_u32_e32 v132, vcc, s14, v0
	s_mov_b32 s14, 0x52e000
	s_nop 0
	v_addc_co_u32_e32 v133, vcc, 0, v1, vcc
	s_waitcnt vmcnt(0)
; __device__ __forceinline__ float ex2(float x) { return __builtin_amdgcn_exp2f(x); }
;     __device__ __forceinline__ void mid(f32x4 (&acc)[2][2][4][2], const pg8::Unit& u, int wr, int wc, int fr, int fq) const {
;         const int row0 = u.pm * 256 + wr * 64 + fr, col0 = u.pn * 256 + wc * 32 + 8 * fq;
;         unsigned base = (unsigned)(row0 * NIN + col0);
;         asm volatile("" : "+v"(base));
;         const half_t* bp0 = P + base;
; #pragma unroll
;         for (int ai = 0; ai < 2; ++ai)
; #pragma unroll
;             for (int m = 0; m < 4; ++m) { const half_t* rowp = bp0 + (size_t)(ai * 128 + m * 16) * NIN;
;                 __builtin_amdgcn_sched_barrier(0);
; #pragma unroll
;                 for (int bj = 0; bj < 2; ++bj) { const h8 ga = *(const h8*)(rowp + C_MR + bj * 128), gb = *(const h8*)(rowp + C_MS + bj * 128);
; #pragma unroll
;                     for (int n = 0; n < 2; ++n)
; #pragma unroll
;                         for (int i = 0; i < 4; ++i) { const float a = (float)ga[4 * n + i], b = (float)gb[4 * n + i];
;                             acc[ai][bj][m][n][i] *= (1.f + ex2(b * -1.44269504f)) * __builtin_amdgcn_rcpf(1.f + ex2(a * -1.44269504f)); } } }
	v_mov_b32_e32 v134, v212
	v_mov_b32_e32 v135, v213
	v_mov_b32_e32 v136, v214
	v_mov_b32_e32 v137, v215
	v_add_co_u32_e32 v0, vcc, s14, v0
	s_nop 1
	v_addc_co_u32_e32 v1, vcc, 0, v1, vcc
	v_mov_b32_e32 v176, v216
	v_mov_b32_e32 v177, v217
	v_mov_b32_e32 v178, v218
	v_mov_b32_e32 v179, v219
	s_nop 0
	v_cvt_f32_f16_e32 v2, v134
	v_mul_f32_e32 v2, 0xbfb8aa3b, v2
	v_exp_f32_e32 v2, v2
	v_cvt_f32_f16_e32 v138, v176
	v_add_f32_e32 v2, 1.0, v2
	v_rcp_f32_e32 v192, v2
	v_cvt_f32_f16_sdwa v2, v134 dst_sel:DWORD dst_unused:UNUSED_PAD src0_sel:WORD_1
	v_cvt_f32_f16_sdwa v134, v176 dst_sel:DWORD dst_unused:UNUSED_PAD src0_sel:WORD_1
	v_mul_f32_e32 v138, 0xbfb8aa3b, v138
	v_exp_f32_e32 v138, v138
	v_mul_f32_e32 v2, 0xbfb8aa3b, v2
	v_exp_f32_e32 v2, v2
	v_mul_f32_e32 v134, 0xbfb8aa3b, v134
	v_exp_f32_e32 v139, v134
	v_cvt_f32_f16_e32 v134, v177
	v_add_f32_e32 v2, 1.0, v2
	v_rcp_f32_e32 v193, v2
	v_cvt_f32_f16_e32 v2, v135
	v_mul_f32_e32 v134, 0xbfb8aa3b, v134
	v_exp_f32_e32 v134, v134
	v_pk_add_f32 v[138:139], v[138:139], 1.0 op_sel_hi:[1,0]
	v_mul_f32_e32 v2, 0xbfb8aa3b, v2
	v_exp_f32_e32 v2, v2
	v_pk_mul_f32 v[138:139], v[138:139], v[192:193]
	v_add_f32_e32 v2, 1.0, v2
	v_rcp_f32_e32 v176, v2
	v_cvt_f32_f16_sdwa v2, v135 dst_sel:DWORD dst_unused:UNUSED_PAD src0_sel:WORD_1
	v_cvt_f32_f16_sdwa v135, v177 dst_sel:DWORD dst_unused:UNUSED_PAD src0_sel:WORD_1
	v_pk_mul_f32 v[16:17], v[16:17], v[138:139]
	v_mul_f32_e32 v2, 0xbfb8aa3b, v2
	v_exp_f32_e32 v2, v2
	v_mul_f32_e32 v135, 0xbfb8aa3b, v135
	v_exp_f32_e32 v135, v135
	v_add_f32_e32 v2, 1.0, v2
	v_rcp_f32_e32 v177, v2
	v_cvt_f32_f16_e32 v2, v136
	v_pk_add_f32 v[134:135], v[134:135], 1.0 op_sel_hi:[1,0]
	v_mul_f32_e32 v2, 0xbfb8aa3b, v2
	v_exp_f32_e32 v2, v2
	v_pk_mul_f32 v[134:135], v[134:135], v[176:177]
	v_add_f32_e32 v2, 1.0, v2
	v_rcp_f32_e32 v138, v2
	v_cvt_f32_f16_sdwa v2, v136 dst_sel:DWORD dst_unused:UNUSED_PAD src0_sel:WORD_1
	v_pk_mul_f32 v[18:19], v[18:19], v[134:135]
	v_cvt_f32_f16_e32 v134, v178
	v_cvt_f32_f16_sdwa v135, v178 dst_sel:DWORD dst_unused:UNUSED_PAD src0_sel:WORD_1
	v_mul_f32_e32 v2, 0xbfb8aa3b, v2
	v_exp_f32_e32 v2, v2
	v_mul_f32_e32 v134, 0xbfb8aa3b, v134
	v_mul_f32_e32 v135, 0xbfb8aa3b, v135
	v_exp_f32_e32 v134, v134
	v_exp_f32_e32 v135, v135
	v_add_f32_e32 v2, 1.0, v2
	v_rcp_f32_e32 v139, v2
	v_cvt_f32_f16_e32 v2, v137
	v_pk_add_f32 v[134:135], v[134:135], 1.0 op_sel_hi:[1,0]
	v_cvt_f32_f16_e32 v136, v179
	v_pk_mul_f32 v[134:135], v[134:135], v[138:139]
	v_mul_f32_e32 v2, 0xbfb8aa3b, v2
	v_pk_mul_f32 v[12:13], v[12:13], v[134:135]
	v_mov_b32_e32 v132, v220
	v_mov_b32_e32 v133, v221
	v_mov_b32_e32 v134, v222
	v_mov_b32_e32 v135, v223
	v_exp_f32_e32 v2, v2
	v_mul_f32_e32 v136, 0xbfb8aa3b, v136
	v_exp_f32_e32 v136, v136
	v_add_f32_e32 v2, 1.0, v2
	v_rcp_f32_e32 v176, v2
	v_cvt_f32_f16_sdwa v2, v137 dst_sel:DWORD dst_unused:UNUSED_PAD src0_sel:WORD_1
	v_cvt_f32_f16_sdwa v137, v179 dst_sel:DWORD dst_unused:UNUSED_PAD src0_sel:WORD_1
	v_mul_f32_e32 v2, 0xbfb8aa3b, v2
	v_exp_f32_e32 v2, v2
	v_mul_f32_e32 v137, 0xbfb8aa3b, v137
	v_exp_f32_e32 v137, v137
	v_add_f32_e32 v2, 1.0, v2
	v_rcp_f32_e32 v177, v2
	v_pk_add_f32 v[136:137], v[136:137], 1.0 op_sel_hi:[1,0]
	s_nop 0
	v_pk_mul_f32 v[136:137], v[136:137], v[176:177]
	s_nop 0
	v_pk_mul_f32 v[14:15], v[14:15], v[136:137]
	v_mov_b32_e32 v136, v224
	v_mov_b32_e32 v137, v225
	v_mov_b32_e32 v138, v226
	v_mov_b32_e32 v139, v227
	s_nop 0
	v_cvt_f32_f16_e32 v2, v132
	v_mul_f32_e32 v1, 0xbfb8aa3b, v2
	v_cvt_f32_f16_sdwa v2, v132 dst_sel:DWORD dst_unused:UNUSED_PAD src0_sel:WORD_1
	v_exp_f32_e32 v1, v1
	v_mul_f32_e32 v2, 0xbfb8aa3b, v2
	v_exp_f32_e32 v2, v2
	v_add_f32_e32 v1, 1.0, v1
	v_rcp_f32_e32 v176, v1
	v_add_f32_e32 v2, 1.0, v2
	v_rcp_f32_e32 v177, v2
	v_cvt_f32_f16_e32 v2, v133
	v_mul_f32_e32 v2, 0xbfb8aa3b, v2
	v_exp_f32_e32 v2, v2
	v_cvt_f32_f16_e32 v0, v136
	v_cvt_f32_f16_sdwa v1, v136 dst_sel:DWORD dst_unused:UNUSED_PAD src0_sel:WORD_1
	v_add_f32_e32 v2, 1.0, v2
	v_rcp_f32_e32 v136, v2
	v_cvt_f32_f16_sdwa v2, v133 dst_sel:DWORD dst_unused:UNUSED_PAD src0_sel:WORD_1
	v_cvt_f32_f16_e32 v132, v137
	v_cvt_f32_f16_sdwa v133, v137 dst_sel:DWORD dst_unused:UNUSED_PAD src0_sel:WORD_1
	v_mul_f32_e32 v0, 0xbfb8aa3b, v0
	v_mul_f32_e32 v2, 0xbfb8aa3b, v2
	v_exp_f32_e32 v2, v2
	v_mul_f32_e32 v132, 0xbfb8aa3b, v132
	v_mul_f32_e32 v133, 0xbfb8aa3b, v133
	v_exp_f32_e32 v132, v132
	v_add_f32_e32 v2, 1.0, v2
	v_rcp_f32_e32 v137, v2
	v_cvt_f32_f16_sdwa v2, v134 dst_sel:DWORD dst_unused:UNUSED_PAD src0_sel:WORD_1
	v_exp_f32_e32 v133, v133
	v_mul_f32_e32 v1, 0xbfb8aa3b, v1
	v_exp_f32_e32 v0, v0
	v_mul_f32_e32 v2, 0xbfb8aa3b, v2
	v_exp_f32_e32 v2, v2
	v_exp_f32_e32 v1, v1
	v_pk_add_f32 v[132:133], v[132:133], 1.0 op_sel_hi:[1,0]
	v_add_f32_e32 v2, 1.0, v2
	v_pk_mul_f32 v[132:133], v[132:133], v[136:137]
	v_pk_add_f32 v[0:1], v[0:1], 1.0 op_sel_hi:[1,0]
	v_pk_mul_f32 v[10:11], v[10:11], v[132:133]
	v_rcp_f32_e32 v133, v2
	v_cvt_f32_f16_e32 v2, v135
	v_pk_mul_f32 v[0:1], v[0:1], v[176:177]
	v_mul_f32_e32 v2, 0xbfb8aa3b, v2
	v_pk_mul_f32 v[8:9], v[8:9], v[0:1]
	v_cvt_f32_f16_e32 v1, v134
	v_exp_f32_e32 v2, v2
	v_cvt_f32_f16_e32 v0, v138
	v_cvt_f32_f16_e32 v134, v139
	v_mul_f32_e32 v1, 0xbfb8aa3b, v1
	v_exp_f32_e32 v1, v1
	v_add_f32_e32 v2, 1.0, v2
	v_rcp_f32_e32 v136, v2
	v_cvt_f32_f16_sdwa v2, v135 dst_sel:DWORD dst_unused:UNUSED_PAD src0_sel:WORD_1
	v_add_f32_e32 v1, 1.0, v1
	v_rcp_f32_e32 v132, v1
	v_cvt_f32_f16_sdwa v1, v138 dst_sel:DWORD dst_unused:UNUSED_PAD src0_sel:WORD_1
	v_cvt_f32_f16_sdwa v135, v139 dst_sel:DWORD dst_unused:UNUSED_PAD src0_sel:WORD_1
	v_mul_f32_e32 v2, 0xbfb8aa3b, v2
	v_exp_f32_e32 v2, v2
	v_mul_f32_e32 v0, 0xbfb8aa3b, v0
	v_mul_f32_e32 v1, 0xbfb8aa3b, v1
	v_mul_f32_e32 v134, 0xbfb8aa3b, v134
	v_mul_f32_e32 v135, 0xbfb8aa3b, v135
	v_exp_f32_e32 v0, v0
	v_exp_f32_e32 v1, v1
	v_exp_f32_e32 v134, v134
	v_exp_f32_e32 v135, v135
	v_add_f32_e32 v2, 1.0, v2
	v_rcp_f32_e32 v137, v2
	v_pk_add_f32 v[0:1], v[0:1], 1.0 op_sel_hi:[1,0]
	v_pk_add_f32 v[134:135], v[134:135], 1.0 op_sel_hi:[1,0]
	v_pk_mul_f32 v[0:1], v[0:1], v[132:133]
	v_pk_mul_f32 v[132:133], v[134:135], v[136:137]
	v_pk_mul_f32 v[4:5], v[4:5], v[0:1]
	v_pk_mul_f32 v[6:7], v[6:7], v[132:133]
	s_branch .LBB0_594
